# attention: K staged one tile ahead (single barrier per KV tile) + QK K-fragment double buffering
# speedup vs baseline: 1.0046x; 1.0045x over previous
; __device__ __forceinline__ int opaque_tid() { int t = threadIdx.x; asm volatile("" : "+v"(t)); return t; }
; __device__ __forceinline__ void attn_body(const bf16_t* Qb, const bf16_t* Kh, const bf16_t* Vh, const bf16_t* Gb, bf16_t* Ob, int seq, char* lds,
;                                           const float* qgain, const float* cosA, const float* sinA, int t0) {
;   const int tid = opaque_tid(), wid = tid >> 6, lane = tid & 63, r32 = lane & 31, hi = lane >> 5;
;   char* V_lds = lds; char* K_lds = lds + 2 * SHM_V;
;   float* ws = (float*)(lds + 2 * SHM_V + 2 * SHM_K) + wid * 64; float* li_l = ws; float* al_l = ws + 32;
;   float m_reg = -1e30f, l_reg = 0; f32x16 o[4] = {}; bf16x8 qr[8];
;   const bf16_t* Qw = Qb + (long)(wid * QBLK + r32) * LDQ + hi * 8;
; #pragma unroll
;   for (int d0 = 0; d0 < 8; ++d0) qr[d0] = ld8(Qw + d0 * 16);
;   {
;     float ss = 0.f;
; #pragma unroll
;     for (int d0 = 0; d0 < 8; ++d0)
; #pragma unroll
;       for (int e = 0; e < 8; ++e) { const float v = bf2f((unsigned short)qr[d0][e]); ss += v * v; }
;     { auto rr = __builtin_amdgcn_permlane32_swap(__float_as_uint(ss), __float_as_uint(ss), false, false); ss = __uint_as_float(rr[0]) + __uint_as_float(rr[1]); }
;     const float rinv = __builtin_amdgcn_rsqf(ss * (1.f / 128) + RMS_EPS);
;     const int t = t0 + wid * QBLK + r32, rp = t >> 6, cp = t & 63;
; #pragma unroll
;     for (int half = 0; half < 2; ++half) { const int pos = half ? cp : rp;
; #pragma unroll
;       for (int dd = 0; dd < 2; ++dd) { const int dx = 4 * half + dd, dy = dx + 2, i0 = 16 * dd + 8 * hi;
;         const f32x4 c0 = *(const f32x4*)(cosA + pos * 32 + i0), c1 = *(const f32x4*)(cosA + pos * 32 + i0 + 4), s0 = *(const f32x4*)(sinA + pos * 32 + i0), s1 = *(const f32x4*)(sinA + pos * 32 + i0 + 4);
;         const f32x4 gx0 = *(const f32x4*)(qgain + 16 * dx + 8 * hi), gx1 = *(const f32x4*)(qgain + 16 * dx + 8 * hi + 4), gy0 = *(const f32x4*)(qgain + 16 * dy + 8 * hi), gy1 = *(const f32x4*)(qgain + 16 * dy + 8 * hi + 4);
.LBB0_258:
	s_lshl_b32 s14, s46, 6
	s_and_b32 s20, s14, 0x300
	s_lshl_b32 s14, s48, 4
	s_and_b32 s38, s47, 0xfffff000
	s_and_b32 s15, s14, 0xfffff000
	s_ashr_i32 s39, s38, 31
	s_mul_i32 s16, s15, 0x2800
	s_mul_hi_i32 s14, s15, 0x2800
	s_add_u32 s19, s4, s16
	s_addc_u32 s21, s5, s14
	s_lshl_b32 s14, s48, 5
	s_and_b32 s17, s14, 0xf00
	s_mul_i32 s14, s17, 0x2800
	s_add_u32 s16, s19, s14
	s_addc_u32 s14, s21, 0
	s_lshl_b32 s18, s48, 8
	s_and_b32 s18, s18, 0x700
	s_and_b32 s22, s48, 0x80
	s_or_b32 s18, s18, s22
	s_lshl_b32 s22, s18, 1
	v_mov_b32_e32 v94, v252
	s_add_u32 s22, s16, s22
	s_addc_u32 s23, s14, 0
	v_ashrrev_i32_e32 v179, 6, v94
	v_and_b32_e32 v181, 31, v94
	v_lshlrev_b32_e32 v178, 5, v179
	v_bfe_u32 v184, v94, 5, 1
	v_or_b32_e32 v95, v178, v181
	v_mov_b64_e32 v[0:1], s[22:23]
	v_mad_i64_i32 v[0:1], s[22:23], v95, s72, v[0:1]
	v_lshlrev_b32_e32 v176, 4, v184
	v_lshl_add_u64 v[4:5], v[0:1], 0, v[176:177]
	s_waitcnt vmcnt(4)
	v_and_b32_e32 v38, 32, v94
	global_load_dwordx4 v[46:49], v[4:5], off offset:224
	global_load_dwordx4 v[54:57], v[4:5], off offset:160
	global_load_dwordx4 v[62:65], v[4:5], off offset:192
	global_load_dwordx4 v[66:69], v[4:5], off offset:128
	global_load_dwordx4 v[8:11], v38, s[40:41] offset:16
	global_load_dwordx4 v[0:3], v38, s[40:41] offset:144
	global_load_dwordx4 v[96:99], v[4:5], off offset:64
	global_load_dwordx4 v[80:83], v[4:5], off offset:96
	global_load_dwordx4 v[100:103], v[4:5], off
	global_load_dwordx4 v[104:107], v[4:5], off offset:32
	v_or_b32_e32 v6, s17, v181
	v_add_u32_e32 v6, v6, v178
	v_ashrrev_i32_e32 v6, 1, v6
	v_and_b32_e32 v6, 0xffffffe0, v6
	v_ashrrev_i32_e32 v7, 31, v6
	v_lshlrev_b64 v[4:5], 2, v[6:7]
	v_mov_b32_e32 v39, v177
	v_lshl_add_u64 v[6:7], s[98:99], 0, v[4:5]
	v_lshl_add_u64 v[4:5], s[24:25], 0, v[4:5]
	v_lshl_add_u64 v[72:73], v[4:5], 0, v[38:39]
	v_lshl_add_u64 v[70:71], v[6:7], 0, v[38:39]
	global_load_dwordx4 v[4:7], v[72:73], off offset:16
	global_load_dwordx4 v[12:15], v[70:71], off offset:16
	global_load_dwordx4 v[28:31], v38, s[40:41]
	global_load_dwordx4 v[24:27], v38, s[40:41] offset:128
	global_load_dwordx4 v[20:23], v[72:73], off
	global_load_dwordx4 v[16:19], v[70:71], off
	s_lshl_b32 s22, s48, 7
	s_and_b32 s22, s22, 0x300
	s_add_u32 s19, s19, s22
	s_addc_u32 s21, s21, 0
	s_add_u32 s36, s19, 0x1000
	s_addc_u32 s37, s21, 0
	s_add_u32 s42, s19, 0x1400
	s_addc_u32 s43, s21, 0
	v_lshlrev_b32_e32 v185, 4, v94
	v_and_b32_e32 v186, 63, v94
	s_add_i32 s19, 0, 0x10000
	s_cmp_lg_u32 0, -1
	s_cselect_b32 s21, 0, 0
	s_mov_b32 s72, s73
	s_mov_b32 s74, s73
	s_mov_b32 s75, s73
	s_mov_b32 s76, s73
	s_mov_b32 s77, s73
	s_mov_b32 s78, s73
	s_mov_b32 s79, s73
	s_mov_b32 s80, s73
	s_mov_b32 s81, s73
	s_mov_b32 s82, s73
	s_mov_b32 s83, s73
	s_mov_b32 s84, s73
	s_mov_b32 s85, s73
	s_mov_b32 s86, s73
	s_mov_b32 s87, s73
	v_mov_b32_e32 v189, 0
	s_waitcnt vmcnt(15)
	v_lshlrev_b32_e32 v35, 16, v49
	v_and_b32_e32 v33, 0xffff0000, v49
	v_lshlrev_b32_e32 v41, 16, v48
	s_waitcnt vmcnt(12)
	v_lshlrev_b32_e32 v52, 16, v69
	s_waitcnt vmcnt(9)
	v_and_b32_e32 v119, 0xffff0000, v97
	s_waitcnt vmcnt(7)
	v_lshlrev_b32_e32 v84, 16, v103
	v_and_b32_e32 v86, 0xffff0000, v103
	v_lshlrev_b32_e32 v103, 16, v97
	v_lshlrev_b32_e32 v121, 16, v96
	v_and_b32_e32 v97, 0xffff0000, v96
	v_and_b32_e32 v96, 0xffff0000, v100
	v_and_b32_e32 v50, 0xffff0000, v69
	v_lshlrev_b32_e32 v60, 16, v67
	v_and_b32_e32 v58, 0xffff0000, v67
	v_lshlrev_b32_e32 v69, 16, v83
	v_and_b32_e32 v67, 0xffff0000, v83
	v_lshlrev_b32_e32 v85, 16, v99
	v_mov_b32_e32 v91, v2
	v_and_b32_e32 v87, 0xffff0000, v99
	v_mov_b32_e32 v2, v11
	v_lshlrev_b32_e32 v75, 16, v82
	v_and_b32_e32 v11, 0xffff0000, v82
	v_lshlrev_b32_e32 v79, 16, v81
	s_waitcnt vmcnt(6)
	v_lshlrev_b32_e32 v78, 16, v105
	v_and_b32_e32 v77, 0xffff0000, v81
	v_and_b32_e32 v76, 0xffff0000, v105
	v_lshlrev_b32_e32 v83, 16, v80
	v_lshlrev_b32_e32 v82, 16, v104
	v_and_b32_e32 v81, 0xffff0000, v80
	v_and_b32_e32 v80, 0xffff0000, v104
	v_lshlrev_b32_e32 v105, 16, v98
	v_lshlrev_b32_e32 v104, 16, v102
	v_and_b32_e32 v99, 0xffff0000, v98
	v_and_b32_e32 v98, 0xffff0000, v102
	v_lshlrev_b32_e32 v102, 16, v101
	v_and_b32_e32 v118, 0xffff0000, v101
	v_lshlrev_b32_e32 v120, 16, v100
	v_pk_mul_f32 v[100:101], v[96:97], v[96:97]
	v_lshlrev_b32_e32 v74, 16, v106
	v_pk_fma_f32 v[124:125], v[120:121], v[120:121], v[100:101]
	v_mov_b32_e32 v90, v10
	v_pk_fma_f32 v[124:125], v[102:103], v[102:103], v[124:125]
	v_and_b32_e32 v10, 0xffff0000, v106
	v_pk_fma_f32 v[124:125], v[118:119], v[118:119], v[124:125]
	v_lshlrev_b32_e32 v40, 16, v56
	v_pk_fma_f32 v[124:125], v[104:105], v[104:105], v[124:125]
	v_and_b32_e32 v37, 0xffff0000, v48
	v_pk_fma_f32 v[124:125], v[98:99], v[98:99], v[124:125]
	v_and_b32_e32 v36, 0xffff0000, v56
	v_pk_fma_f32 v[124:125], v[84:85], v[84:85], v[124:125]
	v_lshlrev_b32_e32 v45, 16, v47
	v_pk_fma_f32 v[124:125], v[86:87], v[86:87], v[124:125]
	v_and_b32_e32 v43, 0xffff0000, v47
	v_pk_fma_f32 v[124:125], v[82:83], v[82:83], v[124:125]
	v_lshlrev_b32_e32 v49, 16, v46
	v_pk_fma_f32 v[124:125], v[80:81], v[80:81], v[124:125]
	v_lshlrev_b32_e32 v48, 16, v54
	v_pk_fma_f32 v[124:125], v[78:79], v[78:79], v[124:125]
	v_and_b32_e32 v47, 0xffff0000, v46
	v_pk_fma_f32 v[124:125], v[76:77], v[76:77], v[124:125]
	v_and_b32_e32 v46, 0xffff0000, v54
	v_pk_fma_f32 v[124:125], v[74:75], v[74:75], v[124:125]
	v_lshlrev_b32_e32 v56, 16, v68
	v_and_b32_e32 v54, 0xffff0000, v68
	v_lshlrev_b32_e32 v68, 16, v107
	v_pk_fma_f32 v[124:125], v[10:11], v[10:11], v[124:125]
	v_lshlrev_b32_e32 v34, 16, v57
	v_and_b32_e32 v32, 0xffff0000, v57
	v_lshlrev_b32_e32 v53, 16, v65
	v_and_b32_e32 v51, 0xffff0000, v65
; __device__ __forceinline__ void attn_body(const bf16_t* Qb, const bf16_t* Kh, const bf16_t* Vh, const bf16_t* Gb, bf16_t* Ob, int seq, char* lds,
;                                           const float* qgain, const float* cosA, const float* sinA, int t0) {
;     ...
;     float ss = 0.f;
; #pragma unroll
;     for (int d0 = 0; d0 < 8; ++d0)
; #pragma unroll
;       for (int e = 0; e < 8; ++e) { const float v = bf2f((unsigned short)qr[d0][e]); ss += v * v; }
;     { auto rr = __builtin_amdgcn_permlane32_swap(__float_as_uint(ss), __float_as_uint(ss), false, false); ss = __uint_as_float(rr[0]) + __uint_as_float(rr[1]); }
;     const float rinv = __builtin_amdgcn_rsqf(ss * (1.f / 128) + RMS_EPS);
;     const int t = t0 + wid * QBLK + r32, rp = t >> 6, cp = t & 63;
; #pragma unroll
;     for (int half = 0; half < 2; ++half) { const int pos = half ? cp : rp;
; #pragma unroll
;       for (int dd = 0; dd < 2; ++dd) { const int dx = 4 * half + dd, dy = dx + 2, i0 = 16 * dd + 8 * hi;
;         const f32x4 c0 = *(const f32x4*)(cosA + pos * 32 + i0), c1 = *(const f32x4*)(cosA + pos * 32 + i0 + 4), s0 = *(const f32x4*)(sinA + pos * 32 + i0), s1 = *(const f32x4*)(sinA + pos * 32 + i0 + 4);
;         const f32x4 gx0 = *(const f32x4*)(qgain + 16 * dx + 8 * hi), gx1 = *(const f32x4*)(qgain + 16 * dx + 8 * hi + 4), gy0 = *(const f32x4*)(qgain + 16 * dy + 8 * hi), gy1 = *(const f32x4*)(qgain + 16 * dy + 8 * hi + 4);
;         float xo[8], yo[8];
; #pragma unroll
;         for (int e = 0; e < 8; ++e) { const float cc = e < 4 ? c0[e & 3] : c1[e & 3], sn = e < 4 ? s0[e & 3] : s1[e & 3];
;           const float x = bf2f((unsigned short)qr[dx][e]) * rinv * (e < 4 ? gx0[e & 3] : gx1[e & 3]), y = bf2f((unsigned short)qr[dy][e]) * rinv * (e < 4 ? gy0[e & 3] : gy1[e & 3]);
;           xo[e] = x * cc - y * sn; yo[e] = y * cc + x * sn; }
	v_lshlrev_b32_e32 v44, 16, v55
	v_and_b32_e32 v42, 0xffff0000, v55
	v_lshlrev_b32_e32 v57, 16, v64
	v_and_b32_e32 v55, 0xffff0000, v64
	v_lshlrev_b32_e32 v61, 16, v63
	v_and_b32_e32 v59, 0xffff0000, v63
	v_lshlrev_b32_e32 v65, 16, v62
	v_lshlrev_b32_e32 v64, 16, v66
	v_and_b32_e32 v63, 0xffff0000, v62
	v_and_b32_e32 v62, 0xffff0000, v66
	v_and_b32_e32 v66, 0xffff0000, v107
	v_pk_fma_f32 v[124:125], v[68:69], v[68:69], v[124:125]
	v_mov_b32_e32 v107, v0
	v_pk_fma_f32 v[124:125], v[66:67], v[66:67], v[124:125]
	v_mul_f32_e32 v0, v121, v121
	v_pk_add_f32 v[124:125], v[0:1], v[124:125] op_sel_hi:[0,1]
	v_pk_add_f32 v[100:101], v[100:101], v[124:125] op_sel:[1,0] op_sel_hi:[0,1]
	v_mul_f32_e32 v0, v103, v103
	v_pk_add_f32 v[100:101], v[0:1], v[100:101] op_sel_hi:[0,1]
	v_mul_f32_e32 v0, v119, v119
	v_pk_add_f32 v[100:101], v[0:1], v[100:101] op_sel_hi:[0,1]
	v_mul_f32_e32 v0, v105, v105
	v_pk_add_f32 v[100:101], v[0:1], v[100:101] op_sel_hi:[0,1]
	v_mul_f32_e32 v0, v99, v99
	v_pk_add_f32 v[100:101], v[0:1], v[100:101] op_sel_hi:[0,1]
	v_mul_f32_e32 v0, v85, v85
	v_pk_add_f32 v[100:101], v[0:1], v[100:101] op_sel_hi:[0,1]
	v_mul_f32_e32 v0, v87, v87
	v_pk_add_f32 v[100:101], v[0:1], v[100:101] op_sel_hi:[0,1]
	v_mul_f32_e32 v0, v83, v83
	v_pk_add_f32 v[100:101], v[0:1], v[100:101] op_sel_hi:[0,1]
	v_mul_f32_e32 v0, v81, v81
	v_pk_add_f32 v[100:101], v[0:1], v[100:101] op_sel_hi:[0,1]
	v_mul_f32_e32 v0, v79, v79
	v_pk_add_f32 v[100:101], v[0:1], v[100:101] op_sel_hi:[0,1]
	v_mul_f32_e32 v0, v77, v77
	v_pk_add_f32 v[100:101], v[0:1], v[100:101] op_sel_hi:[0,1]
	v_mul_f32_e32 v0, v75, v75
	v_pk_add_f32 v[100:101], v[0:1], v[100:101] op_sel_hi:[0,1]
	v_mul_f32_e32 v0, v11, v11
	v_pk_add_f32 v[100:101], v[0:1], v[100:101] op_sel_hi:[0,1]
	v_mul_f32_e32 v0, v69, v69
	v_pk_add_f32 v[100:101], v[0:1], v[100:101] op_sel_hi:[0,1]
	v_mul_f32_e32 v0, v67, v67
	v_pk_add_f32 v[100:101], v[0:1], v[100:101] op_sel_hi:[0,1]
	v_pk_fma_f32 v[100:101], v[64:65], v[64:65], v[100:101]
	v_mul_f32_e32 v0, v65, v65
	v_pk_fma_f32 v[100:101], v[62:63], v[62:63], v[100:101]
	v_mov_b32_e32 v110, v37
	v_pk_fma_f32 v[100:101], v[60:61], v[60:61], v[100:101]
	v_mov_b32_e32 v111, v41
	v_pk_fma_f32 v[100:101], v[58:59], v[58:59], v[100:101]
	v_mov_b32_e32 v108, v33
	v_pk_fma_f32 v[100:101], v[56:57], v[56:57], v[100:101]
	v_mov_b32_e32 v109, v35
	v_pk_fma_f32 v[100:101], v[54:55], v[54:55], v[100:101]
	v_mov_b32_e32 v106, v8
	v_pk_fma_f32 v[100:101], v[52:53], v[52:53], v[100:101]
	s_waitcnt vmcnt(2)
	v_mov_b32_e32 v123, v24
	v_pk_fma_f32 v[100:101], v[50:51], v[50:51], v[100:101]
	v_mov_b32_e32 v24, v29
	v_pk_fma_f32 v[100:101], v[48:49], v[48:49], v[100:101]
	v_mov_b32_e32 v114, v30
	v_pk_fma_f32 v[100:101], v[46:47], v[46:47], v[100:101]
	v_mov_b32_e32 v115, v26
	v_pk_fma_f32 v[100:101], v[44:45], v[44:45], v[100:101]
	v_mov_b32_e32 v122, v28
	v_pk_fma_f32 v[100:101], v[42:43], v[42:43], v[100:101]
	s_waitcnt vmcnt(1)
	v_mov_b32_e32 v116, v22
	v_pk_fma_f32 v[100:101], v[40:41], v[40:41], v[100:101]
	s_waitcnt vmcnt(0)
	v_mov_b32_e32 v117, v18
	v_pk_fma_f32 v[100:101], v[36:37], v[36:37], v[100:101]
	v_mov_b32_e32 v26, v31
	v_pk_fma_f32 v[100:101], v[34:35], v[34:35], v[100:101]
	v_mov_b32_e32 v112, v4
	v_pk_fma_f32 v[100:101], v[32:33], v[32:33], v[100:101]
	v_mov_b32_e32 v113, v12
	v_pk_add_f32 v[100:101], v[0:1], v[100:101] op_sel_hi:[0,1]
	v_mul_f32_e32 v0, v63, v63
	v_pk_add_f32 v[100:101], v[0:1], v[100:101] op_sel_hi:[0,1]
	v_mul_f32_e32 v0, v61, v61
	v_pk_add_f32 v[100:101], v[0:1], v[100:101] op_sel_hi:[0,1]
	v_mul_f32_e32 v0, v59, v59
	v_pk_add_f32 v[100:101], v[0:1], v[100:101] op_sel_hi:[0,1]
	v_mul_f32_e32 v0, v57, v57
	v_pk_add_f32 v[100:101], v[0:1], v[100:101] op_sel_hi:[0,1]
	v_mul_f32_e32 v0, v55, v55
	v_pk_add_f32 v[100:101], v[0:1], v[100:101] op_sel_hi:[0,1]
	v_mul_f32_e32 v0, v53, v53
	v_pk_add_f32 v[100:101], v[0:1], v[100:101] op_sel_hi:[0,1]
	v_mul_f32_e32 v0, v51, v51
	v_pk_add_f32 v[100:101], v[0:1], v[100:101] op_sel_hi:[0,1]
	v_mul_f32_e32 v0, v49, v49
	v_pk_add_f32 v[100:101], v[0:1], v[100:101] op_sel_hi:[0,1]
	v_mul_f32_e32 v0, v47, v47
	v_pk_add_f32 v[100:101], v[0:1], v[100:101] op_sel_hi:[0,1]
	v_mul_f32_e32 v0, v45, v45
	v_pk_add_f32 v[100:101], v[0:1], v[100:101] op_sel_hi:[0,1]
	v_mul_f32_e32 v0, v43, v43
	v_pk_add_f32 v[100:101], v[0:1], v[100:101] op_sel_hi:[0,1]
	v_mul_f32_e32 v0, v41, v41
	v_pk_add_f32 v[100:101], v[0:1], v[100:101] op_sel_hi:[0,1]
	v_pk_fma_f32 v[100:101], v[110:111], v[110:111], v[100:101]
	v_mul_f32_e32 v0, v35, v35
	v_pk_add_f32 v[100:101], v[0:1], v[100:101] op_sel_hi:[0,1]
	v_pk_fma_f32 v[100:101], v[108:109], v[108:109], v[100:101]
	v_mov_b32_e32 v110, v16
	v_mov_b32_e32 v0, v100
	s_nop 1
	v_permlane32_swap_b32_e32 v100, v0
	v_add_f32_e32 v0, v100, v0
	v_fmamk_f32 v0, v0, 0x3c000000, v244
	v_rsq_f32_e32 v8, v0
	v_mov_b32_e32 v101, v16
	v_mov_b32_e32 v16, v21
	v_mov_b32_e32 v100, v20
	v_pk_mul_f32 v[96:97], v[8:9], v[96:97] op_sel_hi:[0,1]
	v_pk_mul_f32 v[24:25], v[24:25], v[96:97]
	v_mov_b32_e32 v111, v20
	v_mov_b32_e32 v20, v17
	v_pk_mul_f32 v[16:17], v[16:17], v[24:25]
	v_pk_mul_f32 v[28:29], v[20:21], v[24:25]
	v_add_f32_e32 v24, v16, v17
	v_pk_mul_f32 v[16:17], v[8:9], v[102:103] op_sel_hi:[0,1]
	v_pk_mul_f32 v[16:17], v[114:115], v[16:17]
	v_mov_b32_e32 v20, v18
	v_mov_b32_e32 v21, v22
	v_pk_mul_f32 v[20:21], v[20:21], v[16:17]
	v_pk_mul_f32 v[16:17], v[116:117], v[16:17]
	v_sub_f32_e32 v28, v28, v29
	v_add_f32_e32 v29, v16, v17
	v_pk_mul_f32 v[16:17], v[8:9], v[118:119] op_sel_hi:[0,1]
	v_pk_mul_f32 v[16:17], v[26:27], v[16:17]
	v_mov_b32_e32 v22, v19
	v_mov_b32_e32 v18, v23
	v_sub_f32_e32 v25, v20, v21
; __device__ __forceinline__ unsigned cvtpk(float lo, float hi) { unsigned r; asm volatile("v_cvt_pk_bf16_f32 %0, %1, %2" : "=v"(r) : "v"(lo), "v"(hi)); return r; }
; __device__ __forceinline__ unsigned cvtpk(float lo, float hi) { unsigned r; asm volatile("v_cvt_pk_bf16_f32 %0, %1, %2" : "=v"(r) : "v"(lo), "v"(hi)); return r; }
; __device__ __forceinline__ void attn_body(const bf16_t* Qb, const bf16_t* Kh, const bf16_t* Vh, const bf16_t* Gb, bf16_t* Ob, int seq, char* lds,
;                                           const float* qgain, const float* cosA, const float* sinA, int t0) {
;     ...
;     for (int half = 0; half < 2; ++half) { const int pos = half ? cp : rp;
; #pragma unroll
;       for (int dd = 0; dd < 2; ++dd) { const int dx = 4 * half + dd, dy = dx + 2, i0 = 16 * dd + 8 * hi;
;         const f32x4 c0 = *(const f32x4*)(cosA + pos * 32 + i0), c1 = *(const f32x4*)(cosA + pos * 32 + i0 + 4), s0 = *(const f32x4*)(sinA + pos * 32 + i0), s1 = *(const f32x4*)(sinA + pos * 32 + i0 + 4);
;         const f32x4 gx0 = *(const f32x4*)(qgain + 16 * dx + 8 * hi), gx1 = *(const f32x4*)(qgain + 16 * dx + 8 * hi + 4), gy0 = *(const f32x4*)(qgain + 16 * dy + 8 * hi), gy1 = *(const f32x4*)(qgain + 16 * dy + 8 * hi + 4);
;         float xo[8], yo[8];
; #pragma unroll
;         for (int e = 0; e < 8; ++e) { const float cc = e < 4 ? c0[e & 3] : c1[e & 3], sn = e < 4 ? s0[e & 3] : s1[e & 3];
;           const float x = bf2f((unsigned short)qr[dx][e]) * rinv * (e < 4 ? gx0[e & 3] : gx1[e & 3]), y = bf2f((unsigned short)qr[dy][e]) * rinv * (e < 4 ? gy0[e & 3] : gy1[e & 3]);
;           xo[e] = x * cc - y * sn; yo[e] = y * cc + x * sn; }
;         u32x4 wx = {cvtpk(xo[0], xo[1]), cvtpk(xo[2], xo[3]), cvtpk(xo[4], xo[5]), cvtpk(xo[6], xo[7])}, wy = {cvtpk(yo[0], yo[1]), cvtpk(yo[2], yo[3]), cvtpk(yo[4], yo[5]), cvtpk(yo[6], yo[7])};
;         qr[dx] = *reinterpret_cast<bf16x8*>(&wx); qr[dy] = *reinterpret_cast<bf16x8*>(&wy); } }
	v_pk_mul_f32 v[20:21], v[22:23], v[16:17]
	v_pk_mul_f32 v[16:17], v[18:19], v[16:17]
	v_sub_f32_e32 v20, v20, v21
	v_add_f32_e32 v21, v16, v17
	v_pk_mul_f32 v[16:17], v[8:9], v[104:105] op_sel_hi:[0,1]
	v_pk_mul_f32 v[16:17], v[16:17], v[106:107]
	v_mov_b32_e32 v18, v12
	v_mov_b32_e32 v19, v4
	v_pk_mul_f32 v[18:19], v[18:19], v[16:17]
	v_pk_mul_f32 v[16:17], v[112:113], v[16:17]
	v_sub_f32_e32 v18, v18, v19
	v_add_f32_e32 v19, v16, v17
	v_pk_mul_f32 v[16:17], v[8:9], v[98:99] op_sel_hi:[0,1]
	v_mov_b32_e32 v0, v9
	v_pk_mul_f32 v[0:1], v[16:17], v[0:1]
	v_mov_b32_e32 v4, v13
	v_pk_mul_f32 v[16:17], v[4:5], v[0:1]
	v_mov_b32_e32 v12, v5
	v_pk_mul_f32 v[108:109], v[8:9], v[120:121] op_sel_hi:[0,1]
	v_sub_f32_e32 v9, v16, v17
	v_pk_mul_f32 v[0:1], v[12:13], v[0:1]
	v_mov_b32_e32 v88, v6
	v_add_f32_e32 v12, v0, v1
	v_pk_mul_f32 v[0:1], v[8:9], v[84:85] op_sel_hi:[0,1]
	v_mov_b32_e32 v89, v14
	v_pk_mul_f32 v[0:1], v[0:1], v[90:91]
	v_mov_b32_e32 v4, v14
	v_mov_b32_e32 v5, v6
	v_pk_mul_f32 v[4:5], v[4:5], v[0:1]
	v_pk_mul_f32 v[0:1], v[88:89], v[0:1]
	v_sub_f32_e32 v4, v4, v5
	v_add_f32_e32 v5, v0, v1
	v_pk_mul_f32 v[0:1], v[8:9], v[86:87] op_sel_hi:[0,1]
	v_pk_mul_f32 v[108:109], v[122:123], v[108:109]
	v_pk_mul_f32 v[0:1], v[0:1], v[2:3]
	v_mov_b32_e32 v6, v15
	v_mov_b32_e32 v92, v7
	v_mov_b32_e32 v93, v15
	v_pk_mul_f32 v[110:111], v[110:111], v[108:109]
	v_pk_mul_f32 v[2:3], v[6:7], v[0:1]
	v_sub_f32_e32 v30, v110, v111
	v_pk_mul_f32 v[100:101], v[100:101], v[108:109]
	v_sub_f32_e32 v2, v2, v3
	v_pk_mul_f32 v[0:1], v[92:93], v[0:1]
	v_add_f32_e32 v108, v100, v101
	v_add_f32_e32 v0, v0, v1
	v_cvt_pk_bf16_f32 v100, v30, v28
	v_cvt_pk_bf16_f32 v101, v25, v20
	v_cvt_pk_bf16_f32 v102, v18, v9
	v_cvt_pk_bf16_f32 v103, v4, v2
	v_cvt_pk_bf16_f32 v96, v108, v24
	v_cvt_pk_bf16_f32 v97, v29, v21
	v_cvt_pk_bf16_f32 v98, v19, v12
	v_cvt_pk_bf16_f32 v99, v5, v0
	global_load_dwordx4 v[2:5], v38, s[40:41] offset:64
	global_load_dwordx4 v[12:15], v38, s[40:41] offset:192
	global_load_dwordx4 v[16:19], v[70:71], off offset:64
	global_load_dwordx4 v[20:23], v[72:73], off offset:64
	global_load_dwordx4 v[24:27], v38, s[40:41] offset:80
	global_load_dwordx4 v[28:31], v38, s[40:41] offset:208
	global_load_dwordx4 v[84:87], v[70:71], off offset:80
	s_nop 0
	global_load_dwordx4 v[70:73], v[72:73], off offset:80
	v_lshlrev_b32_e32 v0, 7, v95
	v_and_b32_e32 v0, 0x1f80, v0
	v_mov_b32_e32 v1, v177
	v_lshl_add_u64 v[6:7], s[98:99], 0, v[0:1]
	v_lshl_add_u64 v[88:89], s[24:25], 0, v[0:1]
	v_lshl_add_u64 v[0:1], v[6:7], 0, v[38:39]
	v_pk_mul_f32 v[6:7], v[8:9], v[82:83] op_sel_hi:[0,1]
	s_waitcnt vmcnt(7)
	v_mov_b32_e32 v82, v2
	s_waitcnt vmcnt(6)
	v_mov_b32_e32 v83, v12
	v_pk_mul_f32 v[6:7], v[6:7], v[82:83]
	s_waitcnt vmcnt(5)
	v_mov_b32_e32 v82, v16
	s_waitcnt vmcnt(4)
	v_mov_b32_e32 v83, v20
	v_pk_mul_f32 v[82:83], v[82:83], v[6:7]
	v_mov_b32_e32 v12, v3
	v_sub_f32_e32 v9, v82, v83
	v_mov_b32_e32 v82, v20
	v_mov_b32_e32 v83, v16
	v_pk_mul_f32 v[6:7], v[82:83], v[6:7]
	v_mov_b32_e32 v20, v17
	v_add_f32_e32 v82, v6, v7
	v_pk_mul_f32 v[6:7], v[8:9], v[80:81] op_sel_hi:[0,1]
	v_pk_mul_f32 v[2:3], v[6:7], v[12:13]
	v_mov_b32_e32 v16, v21
	v_pk_mul_f32 v[6:7], v[20:21], v[2:3]
	v_pk_mul_f32 v[2:3], v[16:17], v[2:3]
	v_sub_f32_e32 v12, v6, v7
	v_add_f32_e32 v13, v2, v3
	v_pk_mul_f32 v[2:3], v[8:9], v[78:79] op_sel_hi:[0,1]
	v_mov_b32_e32 v6, v4
	v_mov_b32_e32 v7, v14
	v_pk_mul_f32 v[2:3], v[2:3], v[6:7]
	v_mov_b32_e32 v6, v18
	v_mov_b32_e32 v7, v22
	v_pk_mul_f32 v[6:7], v[6:7], v[2:3]
	v_mov_b32_e32 v14, v5
	v_sub_f32_e32 v16, v6, v7
	v_mov_b32_e32 v6, v22
	v_mov_b32_e32 v7, v18
	v_pk_mul_f32 v[2:3], v[6:7], v[2:3]
	v_mov_b32_e32 v22, v19
	v_add_f32_e32 v6, v2, v3
	v_pk_mul_f32 v[2:3], v[8:9], v[76:77] op_sel_hi:[0,1]
	v_pk_mul_f32 v[2:3], v[2:3], v[14:15]
	v_mov_b32_e32 v18, v23
	v_pk_mul_f32 v[4:5], v[22:23], v[2:3]
	v_pk_mul_f32 v[2:3], v[18:19], v[2:3]
	v_sub_f32_e32 v7, v4, v5
	v_add_f32_e32 v14, v2, v3
	v_pk_mul_f32 v[2:3], v[8:9], v[74:75] op_sel_hi:[0,1]
	s_waitcnt vmcnt(3)
	v_mov_b32_e32 v4, v24
	s_waitcnt vmcnt(2)
	v_mov_b32_e32 v5, v28
	v_pk_mul_f32 v[2:3], v[2:3], v[4:5]
	s_waitcnt vmcnt(1)
	v_mov_b32_e32 v4, v84
	s_waitcnt vmcnt(0)
	v_mov_b32_e32 v5, v70
	v_pk_mul_f32 v[4:5], v[4:5], v[2:3]
	v_mov_b32_e32 v28, v25
	v_sub_f32_e32 v15, v4, v5
	v_mov_b32_e32 v4, v70
	v_mov_b32_e32 v5, v84
	v_pk_mul_f32 v[2:3], v[4:5], v[2:3]
	v_mov_b32_e32 v70, v85
	v_add_f32_e32 v17, v2, v3
	v_pk_mul_f32 v[2:3], v[8:9], v[10:11] op_sel_hi:[0,1]
	v_pk_mul_f32 v[2:3], v[2:3], v[28:29]
	v_mov_b32_e32 v84, v71
	v_pk_mul_f32 v[4:5], v[70:71], v[2:3]
	v_pk_mul_f32 v[2:3], v[84:85], v[2:3]
	v_sub_f32_e32 v10, v4, v5
	v_add_f32_e32 v11, v2, v3
	v_pk_mul_f32 v[2:3], v[8:9], v[68:69] op_sel_hi:[0,1]
	v_mov_b32_e32 v4, v26
	v_mov_b32_e32 v5, v30
	v_pk_mul_f32 v[2:3], v[2:3], v[4:5]
	v_mov_b32_e32 v4, v86
	v_mov_b32_e32 v5, v72
	v_pk_mul_f32 v[4:5], v[4:5], v[2:3]
	v_mov_b32_e32 v30, v27
	v_sub_f32_e32 v18, v4, v5
	v_mov_b32_e32 v4, v72
	v_mov_b32_e32 v5, v86
	v_pk_mul_f32 v[2:3], v[4:5], v[2:3]
	v_mov_b32_e32 v72, v87
	v_add_f32_e32 v19, v2, v3
	v_pk_mul_f32 v[2:3], v[8:9], v[66:67] op_sel_hi:[0,1]
	v_pk_mul_f32 v[2:3], v[2:3], v[30:31]
	v_mov_b32_e32 v86, v73
	v_pk_mul_f32 v[4:5], v[72:73], v[2:3]
	v_pk_mul_f32 v[2:3], v[86:87], v[2:3]
	v_sub_f32_e32 v4, v4, v5
	v_add_f32_e32 v2, v2, v3
	v_cvt_pk_bf16_f32 v108, v9, v12
	v_cvt_pk_bf16_f32 v109, v16, v7
	v_cvt_pk_bf16_f32 v110, v15, v10
	v_cvt_pk_bf16_f32 v111, v18, v4
	v_cvt_pk_bf16_f32 v104, v82, v13
	v_cvt_pk_bf16_f32 v105, v6, v14
	v_cvt_pk_bf16_f32 v106, v17, v11
	v_cvt_pk_bf16_f32 v107, v19, v2
	global_load_dwordx4 v[2:5], v38, s[40:41] offset:256
	global_load_dwordx4 v[10:13], v38, s[40:41] offset:384
	v_lshl_add_u64 v[6:7], v[88:89], 0, v[38:39]
	global_load_dwordx4 v[14:17], v[0:1], off
	global_load_dwordx4 v[18:21], v[6:7], off
	global_load_dwordx4 v[22:25], v38, s[40:41] offset:272
	global_load_dwordx4 v[26:29], v38, s[40:41] offset:400
	global_load_dwordx4 v[66:69], v[0:1], off offset:16
	global_load_dwordx4 v[70:73], v[6:7], off offset:16
	v_pk_mul_f32 v[30:31], v[8:9], v[64:65] op_sel_hi:[0,1]
	s_waitcnt vmcnt(7)
; __device__ __forceinline__ unsigned cvtpk(float lo, float hi) { unsigned r; asm volatile("v_cvt_pk_bf16_f32 %0, %1, %2" : "=v"(r) : "v"(lo), "v"(hi)); return r; }
; __device__ __forceinline__ unsigned cvtpk(float lo, float hi) { unsigned r; asm volatile("v_cvt_pk_bf16_f32 %0, %1, %2" : "=v"(r) : "v"(lo), "v"(hi)); return r; }
; __device__ __forceinline__ void attn_body(const bf16_t* Qb, const bf16_t* Kh, const bf16_t* Vh, const bf16_t* Gb, bf16_t* Ob, int seq, char* lds,
;                                           const float* qgain, const float* cosA, const float* sinA, int t0) {
;     ...
;     for (int half = 0; half < 2; ++half) { const int pos = half ? cp : rp;
; #pragma unroll
;       for (int dd = 0; dd < 2; ++dd) { const int dx = 4 * half + dd, dy = dx + 2, i0 = 16 * dd + 8 * hi;
;         const f32x4 c0 = *(const f32x4*)(cosA + pos * 32 + i0), c1 = *(const f32x4*)(cosA + pos * 32 + i0 + 4), s0 = *(const f32x4*)(sinA + pos * 32 + i0), s1 = *(const f32x4*)(sinA + pos * 32 + i0 + 4);
;         const f32x4 gx0 = *(const f32x4*)(qgain + 16 * dx + 8 * hi), gx1 = *(const f32x4*)(qgain + 16 * dx + 8 * hi + 4), gy0 = *(const f32x4*)(qgain + 16 * dy + 8 * hi), gy1 = *(const f32x4*)(qgain + 16 * dy + 8 * hi + 4);
;         float xo[8], yo[8];
; #pragma unroll
;         for (int e = 0; e < 8; ++e) { const float cc = e < 4 ? c0[e & 3] : c1[e & 3], sn = e < 4 ? s0[e & 3] : s1[e & 3];
;           const float x = bf2f((unsigned short)qr[dx][e]) * rinv * (e < 4 ? gx0[e & 3] : gx1[e & 3]), y = bf2f((unsigned short)qr[dy][e]) * rinv * (e < 4 ? gy0[e & 3] : gy1[e & 3]);
;           xo[e] = x * cc - y * sn; yo[e] = y * cc + x * sn; }
;         u32x4 wx = {cvtpk(xo[0], xo[1]), cvtpk(xo[2], xo[3]), cvtpk(xo[4], xo[5]), cvtpk(xo[6], xo[7])}, wy = {cvtpk(yo[0], yo[1]), cvtpk(yo[2], yo[3]), cvtpk(yo[4], yo[5]), cvtpk(yo[6], yo[7])};
;         qr[dx] = *reinterpret_cast<bf16x8*>(&wx); qr[dy] = *reinterpret_cast<bf16x8*>(&wy); } }
	v_mov_b32_e32 v64, v2
	s_waitcnt vmcnt(6)
	v_mov_b32_e32 v65, v10
	v_pk_mul_f32 v[30:31], v[30:31], v[64:65]
	s_waitcnt vmcnt(5)
	v_mov_b32_e32 v64, v14
	s_waitcnt vmcnt(4)
	v_mov_b32_e32 v65, v18
	v_pk_mul_f32 v[64:65], v[64:65], v[30:31]
	v_mov_b32_e32 v10, v3
	v_sub_f32_e32 v9, v64, v65
	v_mov_b32_e32 v64, v18
	v_mov_b32_e32 v65, v14
	v_pk_mul_f32 v[30:31], v[64:65], v[30:31]
	v_mov_b32_e32 v18, v15
	v_add_f32_e32 v39, v30, v31
	v_pk_mul_f32 v[30:31], v[8:9], v[62:63] op_sel_hi:[0,1]
	v_pk_mul_f32 v[2:3], v[30:31], v[10:11]
	v_mov_b32_e32 v14, v19
	v_pk_mul_f32 v[10:11], v[18:19], v[2:3]
	v_pk_mul_f32 v[2:3], v[14:15], v[2:3]
	v_sub_f32_e32 v18, v10, v11
	v_add_f32_e32 v14, v2, v3
	v_pk_mul_f32 v[2:3], v[8:9], v[60:61] op_sel_hi:[0,1]
	v_mov_b32_e32 v10, v4
	v_mov_b32_e32 v11, v12
	v_pk_mul_f32 v[2:3], v[2:3], v[10:11]
	v_mov_b32_e32 v10, v16
	v_mov_b32_e32 v11, v20
	v_pk_mul_f32 v[10:11], v[10:11], v[2:3]
	v_mov_b32_e32 v12, v5
	v_sub_f32_e32 v15, v10, v11
	v_mov_b32_e32 v10, v20
	v_mov_b32_e32 v11, v16
	v_pk_mul_f32 v[2:3], v[10:11], v[2:3]
	v_mov_b32_e32 v20, v17
	v_add_f32_e32 v10, v2, v3
	v_pk_mul_f32 v[2:3], v[8:9], v[58:59] op_sel_hi:[0,1]
	v_pk_mul_f32 v[2:3], v[2:3], v[12:13]
	v_mov_b32_e32 v16, v21
	v_pk_mul_f32 v[4:5], v[20:21], v[2:3]
	v_pk_mul_f32 v[2:3], v[16:17], v[2:3]
	v_sub_f32_e32 v11, v4, v5
	v_add_f32_e32 v12, v2, v3
	v_pk_mul_f32 v[2:3], v[8:9], v[56:57] op_sel_hi:[0,1]
	s_waitcnt vmcnt(3)
	v_mov_b32_e32 v4, v22
	s_waitcnt vmcnt(2)
	v_mov_b32_e32 v5, v26
	v_pk_mul_f32 v[2:3], v[2:3], v[4:5]
	s_waitcnt vmcnt(1)
	v_mov_b32_e32 v4, v66
	s_waitcnt vmcnt(0)
	v_mov_b32_e32 v5, v70
	v_pk_mul_f32 v[4:5], v[4:5], v[2:3]
	v_mov_b32_e32 v26, v23
	v_sub_f32_e32 v13, v4, v5
	v_mov_b32_e32 v4, v70
	v_mov_b32_e32 v5, v66
	v_pk_mul_f32 v[2:3], v[4:5], v[2:3]
	v_mov_b32_e32 v70, v67
	v_add_f32_e32 v16, v2, v3
	v_pk_mul_f32 v[2:3], v[8:9], v[54:55] op_sel_hi:[0,1]
	v_pk_mul_f32 v[2:3], v[2:3], v[26:27]
	v_mov_b32_e32 v66, v71
	v_pk_mul_f32 v[4:5], v[70:71], v[2:3]
	v_pk_mul_f32 v[2:3], v[66:67], v[2:3]
	v_sub_f32_e32 v17, v4, v5
	v_add_f32_e32 v19, v2, v3
	v_pk_mul_f32 v[2:3], v[8:9], v[52:53] op_sel_hi:[0,1]
	v_mov_b32_e32 v4, v24
	v_mov_b32_e32 v5, v28
	v_pk_mul_f32 v[2:3], v[2:3], v[4:5]
	v_mov_b32_e32 v4, v68
	v_mov_b32_e32 v5, v72
	v_pk_mul_f32 v[4:5], v[4:5], v[2:3]
	v_mov_b32_e32 v28, v25
	v_sub_f32_e32 v20, v4, v5
	v_mov_b32_e32 v4, v72
	v_mov_b32_e32 v5, v68
	v_pk_mul_f32 v[2:3], v[4:5], v[2:3]
	v_mov_b32_e32 v72, v69
	v_add_f32_e32 v21, v2, v3
	v_pk_mul_f32 v[2:3], v[8:9], v[50:51] op_sel_hi:[0,1]
	v_pk_mul_f32 v[2:3], v[2:3], v[28:29]
	v_mov_b32_e32 v68, v73
	v_pk_mul_f32 v[4:5], v[72:73], v[2:3]
	v_pk_mul_f32 v[2:3], v[68:69], v[2:3]
	v_sub_f32_e32 v4, v4, v5
	v_add_f32_e32 v2, v2, v3
	v_cvt_pk_bf16_f32 v116, v9, v18
	v_cvt_pk_bf16_f32 v117, v15, v11
	v_cvt_pk_bf16_f32 v118, v13, v17
	v_cvt_pk_bf16_f32 v119, v20, v4
	v_cvt_pk_bf16_f32 v112, v39, v14
	v_cvt_pk_bf16_f32 v113, v10, v12
	v_cvt_pk_bf16_f32 v114, v16, v19
	v_cvt_pk_bf16_f32 v115, v21, v2
	global_load_dwordx4 v[2:5], v38, s[40:41] offset:320
	global_load_dwordx4 v[10:13], v38, s[40:41] offset:448
	global_load_dwordx4 v[14:17], v[0:1], off offset:64
	global_load_dwordx4 v[18:21], v[6:7], off offset:64
	global_load_dwordx4 v[22:25], v38, s[40:41] offset:336
	global_load_dwordx4 v[26:29], v38, s[40:41] offset:464
	global_load_dwordx4 v[50:53], v[0:1], off offset:80
	global_load_dwordx4 v[54:57], v[6:7], off offset:80
	v_pk_mul_f32 v[0:1], v[8:9], v[48:49] op_sel_hi:[0,1]
	v_ashrrev_i32_e32 v48, 4, v94
	v_add_u32_e32 v66, 0x80, v48
	v_mad_i64_i32 v[66:67], s[22:23], v66, s69, 0
	v_add_u32_e32 v70, 0xa0, v48
	v_mad_i64_i32 v[70:71], s[22:23], v70, s69, 0
	v_ashrrev_i32_e32 v49, 31, v48
	s_waitcnt vmcnt(7)
	v_mov_b32_e32 v6, v2
	s_waitcnt vmcnt(6)
	v_mov_b32_e32 v7, v10
	v_pk_mul_f32 v[0:1], v[0:1], v[6:7]
	s_waitcnt vmcnt(5)
	v_mov_b32_e32 v6, v14
	s_waitcnt vmcnt(4)
	v_mov_b32_e32 v7, v18
	v_pk_mul_f32 v[6:7], v[6:7], v[0:1]
	v_mov_b32_e32 v10, v3
	v_sub_f32_e32 v9, v6, v7
	v_mov_b32_e32 v6, v18
	v_mov_b32_e32 v7, v14
	v_pk_mul_f32 v[0:1], v[6:7], v[0:1]
	v_mov_b32_e32 v18, v15
	v_add_f32_e32 v6, v0, v1
	v_pk_mul_f32 v[0:1], v[8:9], v[46:47] op_sel_hi:[0,1]
	v_pk_mul_f32 v[0:1], v[0:1], v[10:11]
	v_mov_b32_e32 v14, v19
	v_pk_mul_f32 v[2:3], v[18:19], v[0:1]
	v_pk_mul_f32 v[0:1], v[14:15], v[0:1]
	v_sub_f32_e32 v7, v2, v3
	v_add_f32_e32 v10, v0, v1
	v_pk_mul_f32 v[0:1], v[8:9], v[44:45] op_sel_hi:[0,1]
	v_mov_b32_e32 v2, v4
	v_mov_b32_e32 v3, v12
	v_pk_mul_f32 v[0:1], v[0:1], v[2:3]
	v_mov_b32_e32 v2, v16
	v_mov_b32_e32 v3, v20
	v_pk_mul_f32 v[2:3], v[2:3], v[0:1]
	v_mov_b32_e32 v12, v5
	v_sub_f32_e32 v4, v2, v3
	v_mov_b32_e32 v2, v20
	v_mov_b32_e32 v3, v16
	v_pk_mul_f32 v[0:1], v[2:3], v[0:1]
	v_mov_b32_e32 v20, v17
	v_add_f32_e32 v11, v0, v1
	v_pk_mul_f32 v[0:1], v[8:9], v[42:43] op_sel_hi:[0,1]
	v_pk_mul_f32 v[0:1], v[0:1], v[12:13]
	v_mov_b32_e32 v16, v21
	v_pk_mul_f32 v[2:3], v[20:21], v[0:1]
	v_pk_mul_f32 v[0:1], v[16:17], v[0:1]
	v_sub_f32_e32 v5, v2, v3
	v_add_f32_e32 v12, v0, v1
	v_pk_mul_f32 v[0:1], v[8:9], v[40:41] op_sel_hi:[0,1]
	s_waitcnt vmcnt(3)
	v_mov_b32_e32 v2, v22
	s_waitcnt vmcnt(2)
	v_mov_b32_e32 v3, v26
	v_pk_mul_f32 v[0:1], v[0:1], v[2:3]
	s_waitcnt vmcnt(1)
	v_mov_b32_e32 v2, v50
	s_waitcnt vmcnt(0)
; __device__ __forceinline__ int v_st(int k, int c) { const int kk = (k & ~0xC) | ((k & 4) << 1) | ((k & 8) >> 1); return ((kk >> 3) * 4 + (c >> 5)) * 512 + ((kk & 7) * 32 + (c & 31)) * 2; }
; __device__ __forceinline__ int v_rd_base(int lane) { return ((lane & 3) << 3) | (((lane >> 2) & 3) << 6) | (((lane >> 4) & 1) << 5) | (((lane >> 5) & 1) << 8); }
; #define SLOAD(i, k0) do { sr_[i].vs0 = ld8(&Vh[(long)((k0) + sr) * LDK + sc]); sr_[i].vs1 = ld8(&Vh[(long)((k0) + 32 + sr) * LDK + sc]); \
;     sr_[i].ks0 = ld8(&Kh[(long)((k0) + sr) * LDK + sc]); sr_[i].ks1 = ld8(&Kh[(long)((k0) + 32 + sr) * LDK + sc]); } while (0)
; #define SWAIT() asm volatile("s_waitcnt vmcnt(4)" ::: "memory")
; __device__ __forceinline__ void qkt(f32x16& p0, f32x16& p1, const char* Ks, const bf16x8* qr, int r32, int hi) {
;   p0 = f32x16{}; p1 = f32x16{};
;   for (int d0 = 0; d0 < 8; ++d0) { int cb = (d0 * 16 + hi * 8) * 2;
;     bf16x8 b0 = *reinterpret_cast<const bf16x8*>(Ks + KSWZ(r32, cb));
;     bf16x8 b1 = *reinterpret_cast<const bf16x8*>(Ks + KSWZ(32 + r32, cb));
;     p0 = __builtin_amdgcn_mfma_f32_32x32x16_bf16(b0, qr[d0], p0, 0, 0, 0);
;     p1 = __builtin_amdgcn_mfma_f32_32x32x16_bf16(b1, qr[d0], p1, 0, 0, 0); }
; }
; __device__ __forceinline__ void attn_body(const bf16_t* Qb, const bf16_t* Kh, const bf16_t* Vh, const bf16_t* Gb, bf16_t* Ob, int seq, char* lds,
;                                           const float* qgain, const float* cosA, const float* sinA, int t0) {
;     ...
;   const int sr = tid >> 4, sc = (tid & 15) * 8, vst0 = v_st(sr, sc), vst1 = v_st(32 + sr, sc);
;   const int vb0 = (int)(uintptr_t)V_lds + v_rd_base(lane);
;   struct { bf16x8 vs0, vs1, ks0, ks1; } sr_[2];
;     ...
;   f32x16 pA0, pA1, pB0, pB1; float mnA, mnB, alA, alB; bf16x8 pa0, pa1, pa2, pa3; const int NT = seq / KVBLK;
;   constexpr int SE = 0, SO = 1;
;   SLOAD(SE, 0); asm volatile("s_waitcnt vmcnt(0)" ::: "memory"); SWRITE(0, SE); __syncthreads();
;   qkt(pA0, pA1, K_lds, qr, r32, hi); partialSM(pA0, pA1, m_reg, mnA, alA);
;   SLOAD(SO, KVBLK); if (2 < NT) SLOAD(SE, 2 * KVBLK);
;   SWAIT(); SWRITE(1, SO); __syncthreads();
	v_mov_b32_e32 v3, v54
	v_pk_mul_f32 v[2:3], v[2:3], v[0:1]
	v_mov_b32_e32 v26, v23
	v_sub_f32_e32 v13, v2, v3
	v_mov_b32_e32 v2, v54
	v_mov_b32_e32 v3, v50
	v_pk_mul_f32 v[0:1], v[2:3], v[0:1]
	v_mov_b32_e32 v54, v51
	v_add_f32_e32 v14, v0, v1
	v_pk_mul_f32 v[0:1], v[8:9], v[36:37] op_sel_hi:[0,1]
	v_pk_mul_f32 v[0:1], v[0:1], v[26:27]
	v_mov_b32_e32 v50, v55
	v_pk_mul_f32 v[2:3], v[54:55], v[0:1]
	v_pk_mul_f32 v[0:1], v[50:51], v[0:1]
	v_sub_f32_e32 v15, v2, v3
	v_add_f32_e32 v16, v0, v1
	v_pk_mul_f32 v[0:1], v[8:9], v[34:35] op_sel_hi:[0,1]
	v_mov_b32_e32 v2, v24
	v_mov_b32_e32 v3, v28
	v_pk_mul_f32 v[0:1], v[0:1], v[2:3]
	v_mov_b32_e32 v2, v52
	v_mov_b32_e32 v3, v56
	v_pk_mul_f32 v[2:3], v[2:3], v[0:1]
	v_mov_b32_e32 v28, v25
	v_sub_f32_e32 v17, v2, v3
	v_mov_b32_e32 v2, v56
	v_mov_b32_e32 v3, v52
	v_pk_mul_f32 v[0:1], v[2:3], v[0:1]
	v_mov_b32_e32 v56, v53
	v_add_f32_e32 v18, v0, v1
	v_pk_mul_f32 v[0:1], v[8:9], v[32:33] op_sel_hi:[0,1]
	v_pk_mul_f32 v[0:1], v[0:1], v[28:29]
	v_mov_b32_e32 v52, v57
	v_pk_mul_f32 v[2:3], v[56:57], v[0:1]
	v_pk_mul_f32 v[0:1], v[52:53], v[0:1]
	v_sub_f32_e32 v2, v2, v3
	v_add_f32_e32 v0, v0, v1
	v_cvt_pk_bf16_f32 v124, v9, v7
	v_cvt_pk_bf16_f32 v125, v4, v5
	v_cvt_pk_bf16_f32 v126, v13, v15
	v_cvt_pk_bf16_f32 v127, v17, v2
	v_cvt_pk_bf16_f32 v120, v6, v10
	v_cvt_pk_bf16_f32 v121, v11, v12
	v_cvt_pk_bf16_f32 v122, v14, v16
	v_lshlrev_b32_e32 v16, 3, v94
	v_cvt_pk_bf16_f32 v123, v18, v0
	v_and_b32_e32 v180, 0x78, v16
	v_mad_i64_i32 v[0:1], s[22:23], v48, s69, 0
	v_or_b32_e32 v0, v0, v180
	v_add_u32_e32 v17, 32, v48
	v_lshlrev_b64 v[8:9], 1, v[0:1]
	v_lshl_add_u64 v[0:1], s[42:43], 0, v[8:9]
	v_mad_i64_i32 v[4:5], s[22:23], v17, s69, 0
	global_load_dwordx4 v[0:3], v[0:1], off
	v_or_b32_e32 v4, v4, v180
	v_lshlrev_b64 v[12:13], 1, v[4:5]
	v_lshl_add_u64 v[4:5], s[42:43], 0, v[12:13]
	v_lshl_add_u64 v[8:9], s[36:37], 0, v[8:9]
	global_load_dwordx4 v[4:7], v[4:5], off
	v_lshl_add_u64 v[12:13], s[36:37], 0, v[12:13]
	global_load_dwordx4 v[8:11], v[8:9], off
	v_and_b32_e32 v18, 0xfffff0, v48
	global_load_dwordx4 v[12:15], v[12:13], off
	v_lshlrev_b32_e32 v19, 1, v48
	v_and_or_b32 v18, v19, 8, v18
	v_lshrrev_b32_e32 v19, 1, v48
	v_lshrrev_b32_e32 v18, 1, v18
	v_bfe_u32 v16, v16, 5, 2
	v_and_b32_e32 v20, 3, v48
	v_or_b32_e32 v18, v18, v16
	v_and_or_b32 v19, v19, 4, v20
	v_lshlrev_b32_e32 v20, 1, v180
	v_and_b32_e32 v22, 0xfffff0, v17
	v_lshlrev_b32_e32 v23, 1, v17
	v_lshlrev_b32_e32 v18, 9, v18
	v_lshlrev_b32_e32 v19, 6, v19
	v_and_b32_e32 v21, 48, v20
	v_and_or_b32 v22, v23, 8, v22
	v_or3_b32 v18, v18, v19, v21
	v_lshrrev_b32_e32 v22, 1, v22
	v_or_b32_e32 v16, v22, v16
	v_add_u32_e32 v192, 0, v18
	v_lshlrev_b32_e32 v16, 9, v16
	s_waitcnt vmcnt(0)
	v_or3_b32 v16, v16, v19, v21
	v_add_u32_e32 v193, 0, v16
	v_or_b32_e32 v66, v66, v180
	v_lshlrev_b64 v[66:67], 1, v[66:67]
	v_or_b32_e32 v70, v70, v180
	v_lshl_add_u64 v[68:69], s[42:43], 0, v[66:67]
	v_lshlrev_b64 v[70:71], 1, v[70:71]
	v_lshl_add_u64 v[66:67], s[36:37], 0, v[66:67]
	v_lshl_add_u64 v[72:73], s[42:43], 0, v[70:71]
	s_waitcnt vmcnt(3)
	ds_write_b128 v192, v[0:3]
	v_lshlrev_b32_e32 v0, 8, v48
	v_and_b32_e32 v1, 0x70, v94
	v_bitop3_b32 v0, v20, v0, v1 bitop3:0xde
	v_add_u32_e32 v199, 0, v0
	v_lshlrev_b32_e32 v0, 8, v17
	s_waitcnt vmcnt(2)
	ds_write_b128 v193, v[4:7]
	s_waitcnt vmcnt(1)
	ds_write_b128 v199, v[8:11] offset:32768
	v_bitop3_b32 v0, v20, v0, v1 bitop3:0xde
	v_lshlrev_b32_e32 v8, 8, v181
	v_and_b32_e32 v9, 0x70, v185
	v_add_u32_e32 v200, 0, v0
	v_bitop3_b32 v0, v176, v8, v9 bitop3:0xde
	v_add_u32_e32 v201, 0, v0
	s_waitcnt vmcnt(0)
	ds_write_b128 v200, v[12:15] offset:32768
	s_waitcnt lgkmcnt(0)
	s_barrier
	ds_read_b128 v[0:3], v201 offset:32768
	ds_read_b128 v[4:7], v201 offset:40960
	s_waitcnt lgkmcnt(1)
	v_mfma_f32_32x32x16_bf16 v[32:47], v[0:3], v[100:103], 0
	v_or_b32_e32 v0, 32, v176
	v_bitop3_b32 v0, v0, v8, v9 bitop3:0xde
	v_add_u32_e32 v204, 0, v0
	v_lshlrev_b32_e32 v10, 3, v186
	s_waitcnt lgkmcnt(0)
	v_mfma_f32_32x32x16_bf16 v[16:31], v[4:7], v[100:103], 0
	ds_read_b128 v[0:3], v204 offset:32768
	ds_read_b128 v[4:7], v204 offset:40960
	s_waitcnt lgkmcnt(1)
	v_mfma_f32_32x32x16_bf16 v[32:47], v[0:3], v[108:111], v[32:47]
	v_or_b32_e32 v0, 64, v176
	v_bitop3_b32 v0, v0, v8, v9 bitop3:0xde
	v_add_u32_e32 v205, 0, v0
	s_waitcnt lgkmcnt(0)
	v_mfma_f32_32x32x16_bf16 v[16:31], v[4:7], v[108:111], v[16:31]
	ds_read_b128 v[0:3], v205 offset:32768
	ds_read_b128 v[4:7], v205 offset:40960
	s_waitcnt lgkmcnt(1)
	v_mfma_f32_32x32x16_bf16 v[32:47], v[0:3], v[96:99], v[32:47]
	v_or_b32_e32 v0, 0x60, v176
	v_bitop3_b32 v0, v0, v8, v9 bitop3:0xde
	v_add_u32_e32 v202, 0, v0
	s_waitcnt lgkmcnt(0)
	v_mfma_f32_32x32x16_bf16 v[16:31], v[4:7], v[96:99], v[16:31]
	ds_read_b128 v[0:3], v202 offset:32768
	ds_read_b128 v[4:7], v202 offset:40960
	s_waitcnt lgkmcnt(1)
	v_mfma_f32_32x32x16_bf16 v[32:47], v[0:3], v[104:107], v[32:47]
	v_or_b32_e32 v0, 0x80, v176
	v_bitop3_b32 v0, v0, v8, v9 bitop3:0xde
	v_add_u32_e32 v203, 0, v0
	s_waitcnt lgkmcnt(0)
	v_mfma_f32_32x32x16_bf16 v[16:31], v[4:7], v[104:107], v[16:31]
	ds_read_b128 v[0:3], v203 offset:32768
	ds_read_b128 v[4:7], v203 offset:40960
	s_waitcnt lgkmcnt(1)
	v_mfma_f32_32x32x16_bf16 v[32:47], v[0:3], v[116:119], v[32:47]
	v_or_b32_e32 v0, 0xa0, v176
	v_bitop3_b32 v0, v0, v8, v9 bitop3:0xde
	v_add_u32_e32 v206, 0, v0
	ds_read_b128 v[0:3], v206 offset:32768
	s_waitcnt lgkmcnt(1)
	v_mfma_f32_32x32x16_bf16 v[16:31], v[4:7], v[116:119], v[16:31]
	v_and_b32_e32 v4, 0x3fffffc0, v94
	v_lshl_add_u32 v187, v4, 2, s19
	v_and_b32_e32 v4, 0xc0, v185
	v_and_or_b32 v11, v10, 24, v4
	ds_read_b128 v[4:7], v206 offset:40960
	v_and_b32_e32 v10, 0x100, v10
	s_mov_b32 s19, -1
	s_waitcnt lgkmcnt(1)
; #define SLOAD(i, k0) do { sr_[i].vs0 = ld8(&Vh[(long)((k0) + sr) * LDK + sc]); sr_[i].vs1 = ld8(&Vh[(long)((k0) + 32 + sr) * LDK + sc]); \
;     sr_[i].ks0 = ld8(&Kh[(long)((k0) + sr) * LDK + sc]); sr_[i].ks1 = ld8(&Kh[(long)((k0) + 32 + sr) * LDK + sc]); } while (0)
; #define SWRITE(b, i) do { *(bf16x8*)(V_lds + (b) * SHM_V + vst0) = sr_[i].vs0;          \
;     *(bf16x8*)(V_lds + (b) * SHM_V + vst1) = sr_[i].vs1; int kc = sc * 2;               \
;     *(bf16x8*)(K_lds + (b) * SHM_K + KSWZ(sr, kc)) = sr_[i].ks0;                       \
;     *(bf16x8*)(K_lds + (b) * SHM_K + KSWZ(32 + sr, kc)) = sr_[i].ks1; } while (0)
; #define SWAIT() asm volatile("s_waitcnt vmcnt(4)" ::: "memory")
; __device__ __forceinline__ void partialSM(f32x16& p0, f32x16& p1, float& m_reg, float& mn, float& alpha) {
;   constexpr float C = SCALE * 1.4426950408889634f;
;   float pmax = p0[0]; for (int r = 1; r < 16; ++r) pmax = fmaxf(pmax, p0[r]); for (int r = 0; r < 16; ++r) pmax = fmaxf(pmax, p1[r]);
;   { auto rr = __builtin_amdgcn_permlane32_swap(__float_as_uint(pmax), __float_as_uint(pmax), false, false);
;     pmax = fmaxf(__uint_as_float(rr[0]), __uint_as_float(rr[1])); }
;   if (__builtin_expect(__all(pmax - m_reg <= THR / SCALE), 1)) { mn = m_reg; alpha = 1.f; }
;   else { mn = fmaxf(m_reg, pmax); alpha = __builtin_amdgcn_exp2f((m_reg - mn) * C); m_reg = mn; }
;   float mnC = -mn * C;
;   for (int r = 0; r < 16; ++r) p0[r] = fmaf(p0[r], C, mnC); for (int r = 0; r < 16; ++r) p1[r] = fmaf(p1[r], C, mnC);
;   for (int r = 0; r < 16; ++r) p0[r] = __builtin_amdgcn_exp2f(p0[r]);
; __device__ __forceinline__ void attn_body(const bf16_t* Qb, const bf16_t* Kh, const bf16_t* Vh, const bf16_t* Gb, bf16_t* Ob, int seq, char* lds,
;                                           const float* qgain, const float* cosA, const float* sinA, int t0) {
;     ...
;   f32x16 pA0, pA1, pB0, pB1; float mnA, mnB, alA, alB; bf16x8 pa0, pa1, pa2, pa3; const int NT = seq / KVBLK;
;   constexpr int SE = 0, SO = 1;
;   SLOAD(SE, 0); asm volatile("s_waitcnt vmcnt(0)" ::: "memory"); SWRITE(0, SE); __syncthreads();
;   qkt(pA0, pA1, K_lds, qr, r32, hi); partialSM(pA0, pA1, m_reg, mnA, alA);
;   SLOAD(SO, KVBLK); if (2 < NT) SLOAD(SE, 2 * KVBLK);
;   SWAIT(); SWRITE(1, SO); __syncthreads();
	v_mfma_f32_32x32x16_bf16 v[32:47], v[0:3], v[124:127], v[32:47]
	v_lshlrev_b32_e32 v0, 1, v94
	v_and_b32_e32 v12, 32, v0
	v_or_b32_e32 v0, 0xc0, v176
	v_bitop3_b32 v0, v0, v8, v9 bitop3:0xde
	v_add_u32_e32 v207, 0, v0
	ds_read_b128 v[0:3], v207 offset:32768
	v_or3_b32 v74, v11, v12, v10
	s_waitcnt lgkmcnt(1)
	v_mfma_f32_32x32x16_bf16 v[16:31], v[4:7], v[124:127], v[16:31]
	ds_read_b128 v[4:7], v207 offset:40960
	v_add_u32_e32 v191, s21, v74
	v_lshl_add_u32 v188, v181, 2, v187
	s_waitcnt lgkmcnt(1)
	v_mfma_f32_32x32x16_bf16 v[32:47], v[0:3], v[112:115], v[32:47]
	v_or_b32_e32 v0, 0xe0, v176
	v_bitop3_b32 v0, v0, v8, v9 bitop3:0xde
	v_add_u32_e32 v208, 0, v0
	ds_read_b128 v[0:3], v208 offset:32768
	ds_read_b128 v[50:53], v208 offset:40960
	s_waitcnt lgkmcnt(2)
	v_mfma_f32_32x32x16_bf16 v[16:31], v[4:7], v[112:115], v[16:31]
	s_waitcnt lgkmcnt(1)
	v_mfma_f32_32x32x16_bf16 v[32:47], v[0:3], v[120:123], v[32:47]
	v_mov_b64_e32 v[0:1], s[72:73]
	v_mov_b64_e32 v[2:3], s[74:75]
	v_mov_b64_e32 v[4:5], s[76:77]
	v_mov_b64_e32 v[6:7], s[78:79]
	v_mov_b64_e32 v[8:9], s[80:81]
	v_mov_b64_e32 v[10:11], s[82:83]
	v_mov_b64_e32 v[12:13], s[84:85]
	s_waitcnt lgkmcnt(0)
	v_mfma_f32_32x32x16_bf16 v[16:31], v[50:53], v[120:123], v[16:31]
	s_nop 2
	v_max_f32_e32 v50, v33, v33
	v_max_f32_e32 v51, v32, v32
	v_max_f32_e32 v50, v51, v50
	v_max3_f32 v50, v50, v34, v35
	v_max3_f32 v50, v50, v36, v37
	v_max3_f32 v50, v50, v38, v39
	v_max3_f32 v50, v50, v40, v41
	v_max3_f32 v50, v50, v42, v43
	v_max3_f32 v50, v50, v44, v45
	v_max3_f32 v50, v50, v46, v47
	v_max3_f32 v50, v50, v16, v17
	v_max3_f32 v50, v50, v18, v19
	v_max3_f32 v50, v50, v20, v21
	v_max3_f32 v50, v50, v22, v23
	v_max3_f32 v50, v50, v24, v25
	v_max3_f32 v50, v50, v26, v27
	v_max3_f32 v50, v50, v28, v29
	v_max3_f32 v75, v50, v30, v31
	v_add_u32_e32 v50, 64, v48
	v_add_u32_e32 v52, 0x60, v48
	v_mad_i64_i32 v[50:51], s[22:23], v50, s69, 0
	v_mad_i64_i32 v[52:53], s[22:23], v52, s69, 0
	v_or_b32_e32 v50, v50, v180
	v_or_b32_e32 v52, v52, v180
	v_lshlrev_b64 v[58:59], 1, v[50:51]
	v_lshlrev_b64 v[60:61], 1, v[52:53]
	v_lshl_add_u64 v[50:51], s[42:43], 0, v[58:59]
	v_lshl_add_u64 v[54:55], s[42:43], 0, v[60:61]
	v_lshl_add_u64 v[58:59], s[36:37], 0, v[58:59]
	v_lshl_add_u64 v[62:63], s[36:37], 0, v[60:61]
	global_load_dwordx4 v[50:53], v[50:51], off
	s_nop 0
	global_load_dwordx4 v[54:57], v[54:55], off
	s_nop 0
	global_load_dwordx4 v[58:61], v[58:59], off
	s_nop 0
	global_load_dwordx4 v[62:65], v[62:63], off
	s_nop 0
	global_load_dwordx4 v[128:131], v[68:69], off
	global_load_dwordx4 v[132:135], v[72:73], off
	v_lshl_add_u64 v[68:69], s[36:37], 0, v[70:71]
	global_load_dwordx4 v[240:243], v[66:67], off
	global_load_dwordx4 v[246:249], v[68:69], off
	v_add_co_u32_e32 v66, vcc, 0xa0000, v66
	s_nop 1
	v_addc_co_u32_e32 v67, vcc, 0, v67, vcc
	v_add_co_u32_e32 v68, vcc, 0xa0000, v68
	s_nop 1
	v_addc_co_u32_e32 v69, vcc, 0, v69, vcc
	global_load_dwordx4 v[136:139], v[66:67], off
	global_load_dwordx4 v[140:143], v[68:69], off
	v_mov_b32_e32 v76, v75
	s_nop 1
	v_permlane32_swap_b32_e32 v75, v76
	v_max_f32_e32 v66, v76, v76
	v_max_f32_e32 v67, v75, v75
	v_max_f32_e32 v66, v67, v66
	v_add_f32_e32 v67, 0x7149f2ca, v66
	v_max_f32_e32 v66, 0xf149f2ca, v66
	v_cmp_ge_f32_e32 vcc, s71, v67
	v_sub_f32_e32 v67, 0xf149f2ca, v66
	v_mul_f32_e32 v67, 0x3e0293ee, v67
	v_exp_f32_e32 v67, v67
	s_cmp_eq_u64 vcc, exec
	s_cselect_b64 vcc, -1, 0
	v_mov_b32_e32 v68, 0xf149f2ca
	v_cndmask_b32_e32 v164, v66, v68, vcc
	v_mul_f32_e32 v66, 0xbe0293ee, v164
	v_cndmask_b32_e64 v209, v67, 1.0, vcc
	v_mov_b32_e32 v67, v66
	v_fmac_f32_e32 v67, 0x3e0293ee, v47
	v_mov_b64_e32 v[14:15], s[86:87]
	s_movk_i32 s72, 0x2800
	v_pk_fma_f32 v[156:157], v[16:17], s[62:63], v[66:67] op_sel_hi:[1,0,0]
	v_lshl_add_u64 v[16:17], v[48:49], 0, s[38:39]
	v_fmamk_f32 v32, v32, 0x3e0293ee, v66
	v_fmamk_f32 v33, v33, 0x3e0293ee, v66
	v_fmamk_f32 v34, v34, 0x3e0293ee, v66
	v_fmamk_f32 v35, v35, 0x3e0293ee, v66
	v_fmamk_f32 v36, v36, 0x3e0293ee, v66
	v_fmamk_f32 v37, v37, 0x3e0293ee, v66
	v_fmamk_f32 v38, v38, 0x3e0293ee, v66
	v_fmamk_f32 v39, v39, 0x3e0293ee, v66
	v_fmamk_f32 v40, v40, 0x3e0293ee, v66
	v_fmamk_f32 v41, v41, 0x3e0293ee, v66
	v_fmamk_f32 v42, v42, 0x3e0293ee, v66
	v_fmamk_f32 v43, v43, 0x3e0293ee, v66
	v_fmamk_f32 v44, v44, 0x3e0293ee, v66
	v_fmamk_f32 v45, v45, 0x3e0293ee, v66
	v_fmamk_f32 v46, v46, 0x3e0293ee, v66
	v_pk_fma_f32 v[154:155], v[18:19], s[62:63], v[66:67] op_sel_hi:[1,0,0]
	v_mad_u64_u32 v[18:19], s[22:23], v16, s72, 0
	v_and_b32_e32 v16, 15, v94
	v_exp_f32_e32 v175, v32
	v_exp_f32_e32 v216, v33
	v_exp_f32_e32 v161, v34
	v_exp_f32_e32 v213, v35
	v_exp_f32_e32 v162, v36
	v_exp_f32_e32 v174, v37
	v_exp_f32_e32 v163, v38
	v_exp_f32_e32 v173, v39
	v_exp_f32_e32 v170, v40
	v_exp_f32_e32 v172, v41
	v_exp_f32_e32 v169, v42
	v_exp_f32_e32 v171, v43
	v_exp_f32_e32 v166, v44
	v_exp_f32_e32 v168, v45
	v_exp_f32_e32 v165, v46
	v_exp_f32_e32 v167, v67
	v_lshlrev_b32_e32 v16, 4, v16
	s_waitcnt vmcnt(4)
	v_mad_i32_i24 v17, v17, s72, v19
	v_or3_b32 v16, v18, s20, v16
	v_pk_fma_f32 v[150:151], v[30:31], s[62:63], v[66:67] op_sel_hi:[1,0,0]
	v_pk_fma_f32 v[152:153], v[28:29], s[62:63], v[66:67] op_sel_hi:[1,0,0]
	v_pk_fma_f32 v[158:159], v[26:27], s[62:63], v[66:67] op_sel_hi:[1,0,0]
	v_pk_fma_f32 v[144:145], v[24:25], s[62:63], v[66:67] op_sel_hi:[1,0,0]
	v_pk_fma_f32 v[146:147], v[22:23], s[62:63], v[66:67] op_sel_hi:[1,0,0]
	v_pk_fma_f32 v[148:149], v[20:21], s[62:63], v[66:67] op_sel_hi:[1,0,0]
	s_waitcnt vmcnt(7)
	ds_write_b128 v192, v[50:53] offset:16384
	s_waitcnt vmcnt(6)
	ds_write_b128 v193, v[54:57] offset:16384
	s_waitcnt vmcnt(5)
	ds_write_b128 v199, v[58:61] offset:49152
	s_waitcnt vmcnt(4)
	ds_write_b128 v200, v[62:65] offset:49152
	s_addk_i32 s21, 0x4000
	v_lshl_add_u64 v[182:183], s[50:51], 0, v[16:17]
	v_mov_b64_e32 v[62:63], v[14:15]
	v_mov_b64_e32 v[46:47], v[14:15]
	v_mov_b64_e32 v[30:31], v[14:15]
	v_cmp_gt_u32_e64 s[36:37], 32, v186
	v_add_u32_e32 v190, s21, v74
	v_mov_b64_e32 v[60:61], v[12:13]
	v_mov_b64_e32 v[58:59], v[10:11]
	v_mov_b64_e32 v[56:57], v[8:9]
	v_mov_b64_e32 v[54:55], v[6:7]
	v_mov_b64_e32 v[52:53], v[4:5]
	v_mov_b64_e32 v[50:51], v[2:3]
	v_mov_b64_e32 v[48:49], v[0:1]
	v_mov_b64_e32 v[44:45], v[12:13]
	v_mov_b64_e32 v[42:43], v[10:11]
	v_mov_b64_e32 v[40:41], v[8:9]
	v_mov_b64_e32 v[38:39], v[6:7]
	v_mov_b64_e32 v[36:37], v[4:5]
	v_mov_b64_e32 v[34:35], v[2:3]
	v_mov_b64_e32 v[32:33], v[0:1]
	v_mov_b64_e32 v[28:29], v[12:13]
	v_mov_b64_e32 v[26:27], v[10:11]
	v_mov_b64_e32 v[24:25], v[8:9]
	v_mov_b64_e32 v[22:23], v[6:7]
	v_mov_b64_e32 v[20:21], v[4:5]
	v_mov_b64_e32 v[18:19], v[2:3]
	v_mov_b64_e32 v[16:17], v[0:1]
	s_waitcnt lgkmcnt(0)
	s_barrier
	s_waitcnt vmcnt(2)
	ds_write_b128 v199, v[240:243] offset:32768
	ds_write_b128 v200, v[246:249] offset:32768
; __device__ __forceinline__ void finishSM(f32x16& p0, f32x16& p1, float alpha, float& l_reg, bf16x8& pa0, bf16x8& pa1, bf16x8& pa2, bf16x8& pa3) {
;   for (int r = 0; r < 16; ++r) p1[r] = __builtin_amdgcn_exp2f(p1[r]);
;   float ps = 0; for (int r = 0; r < 16; ++r) ps += p0[r]; for (int r = 0; r < 16; ++r) ps += p1[r];
;   { auto rr = __builtin_amdgcn_permlane32_swap(__float_as_uint(ps), __float_as_uint(ps), false, false);
;     ps = __uint_as_float(rr[0]) + __uint_as_float(rr[1]); }
;   l_reg = l_reg * alpha + ps;
;     ...
;   PK4(p0, 0, pa0); PK4(p0, 8, pa1); PK4(p1, 0, pa2); PK4(p1, 8, pa3);
;     ...
; }
; __device__ __forceinline__ void qkt(f32x16& p0, f32x16& p1, const char* Ks, const bf16x8* qr, int r32, int hi) {
;   p0 = f32x16{}; p1 = f32x16{};
;   for (int d0 = 0; d0 < 8; ++d0) { int cb = (d0 * 16 + hi * 8) * 2;
;     bf16x8 b0 = *reinterpret_cast<const bf16x8*>(Ks + KSWZ(r32, cb));
;     bf16x8 b1 = *reinterpret_cast<const bf16x8*>(Ks + KSWZ(32 + r32, cb));
;     p0 = __builtin_amdgcn_mfma_f32_32x32x16_bf16(b0, qr[d0], p0, 0, 0, 0);
;     p1 = __builtin_amdgcn_mfma_f32_32x32x16_bf16(b1, qr[d0], p1, 0, 0, 0); }
; }
.LBB0_259:
	ds_read_b128 v[64:67], v201 offset:49152
	ds_read_b128 v[68:71], v201 offset:57344
	ds_read_b128 v[218:221], v204 offset:49152
	ds_read_b128 v[222:225], v204 offset:57344
	ds_read_b128 v[240:243], v205 offset:49152
	ds_read_b128 v[246:249], v205 offset:57344
	v_add_f32_e32 v160, 0, v175
	v_add_f32_e32 v160, v216, v160
	s_waitcnt lgkmcnt(5)
	v_mfma_f32_32x32x16_bf16 v[80:95], v[64:67], v[100:103], 0
	v_add_f32_e32 v160, v161, v160
	v_add_f32_e32 v160, v213, v160
	v_add_f32_e32 v160, v162, v160
	v_add_f32_e32 v160, v174, v160
	v_add_f32_e32 v160, v163, v160
	v_add_f32_e32 v160, v173, v160
	v_add_f32_e32 v160, v170, v160
	s_waitcnt lgkmcnt(4)
	v_mfma_f32_32x32x16_bf16 v[64:79], v[68:71], v[100:103], 0
	v_add_f32_e32 v160, v172, v160
	v_add_f32_e32 v160, v169, v160
	v_add_f32_e32 v160, v171, v160
	v_exp_f32_e32 v156, v156
	v_add_f32_e32 v160, v166, v160
	v_exp_f32_e32 v157, v157
	v_add_f32_e32 v160, v168, v160
	s_waitcnt lgkmcnt(3)
	v_mfma_f32_32x32x16_bf16 v[80:95], v[218:221], v[108:111], v[80:95]
	v_exp_f32_e32 v154, v154
	v_add_f32_e32 v160, v165, v160
	v_exp_f32_e32 v155, v155
	v_add_f32_e32 v160, v167, v160
	v_exp_f32_e32 v148, v148
	v_add_f32_e32 v160, v156, v160
	v_exp_f32_e32 v149, v149
	s_waitcnt lgkmcnt(2)
	v_mfma_f32_32x32x16_bf16 v[64:79], v[222:225], v[108:111], v[64:79]
	ds_read_b128 v[218:221], v202 offset:49152
	ds_read_b128 v[222:225], v202 offset:57344
	v_add_f32_e32 v160, v157, v160
	v_exp_f32_e32 v146, v146
	v_add_f32_e32 v160, v154, v160
	v_exp_f32_e32 v147, v147
	v_add_f32_e32 v160, v155, v160
	v_exp_f32_e32 v144, v144
	s_waitcnt lgkmcnt(3)
	v_mfma_f32_32x32x16_bf16 v[80:95], v[240:243], v[96:99], v[80:95]
	v_add_f32_e32 v160, v148, v160
	v_exp_f32_e32 v145, v145
	v_add_f32_e32 v160, v149, v160
	v_exp_f32_e32 v158, v158
	v_add_f32_e32 v160, v146, v160
	v_exp_f32_e32 v159, v159
	v_add_f32_e32 v160, v147, v160
	s_waitcnt lgkmcnt(2)
	v_mfma_f32_32x32x16_bf16 v[64:79], v[246:249], v[96:99], v[64:79]
	ds_read_b128 v[240:243], v203 offset:49152
	ds_read_b128 v[246:249], v203 offset:57344
	v_exp_f32_e32 v152, v152
	v_add_f32_e32 v160, v144, v160
	v_exp_f32_e32 v153, v153
	v_add_f32_e32 v160, v145, v160
	v_exp_f32_e32 v150, v150
	v_add_f32_e32 v160, v158, v160
	s_waitcnt lgkmcnt(3)
	v_mfma_f32_32x32x16_bf16 v[80:95], v[218:221], v[104:107], v[80:95]
	v_exp_f32_e32 v151, v151
	v_add_f32_e32 v160, v159, v160
	v_add_f32_e32 v160, v152, v160
	v_add_f32_e32 v160, v153, v160
	v_add_f32_e32 v160, v150, v160
	v_add_f32_e32 v210, v151, v160
	v_mov_b32_e32 v211, v210
	s_waitcnt lgkmcnt(2)
	v_mfma_f32_32x32x16_bf16 v[64:79], v[222:225], v[104:107], v[64:79]
	ds_read_b128 v[218:221], v206 offset:49152
	ds_read_b128 v[222:225], v206 offset:57344
	v_permlane32_swap_b32_e32 v210, v211
	s_waitcnt lgkmcnt(3)
	v_mfma_f32_32x32x16_bf16 v[80:95], v[240:243], v[116:119], v[80:95]
	s_waitcnt lgkmcnt(2)
	v_mfma_f32_32x32x16_bf16 v[64:79], v[246:249], v[116:119], v[64:79]
	ds_read_b128 v[240:243], v207 offset:49152
	ds_read_b128 v[246:249], v207 offset:57344
	s_waitcnt lgkmcnt(3)
	v_mfma_f32_32x32x16_bf16 v[80:95], v[218:221], v[124:127], v[80:95]
	s_waitcnt lgkmcnt(2)
	v_mfma_f32_32x32x16_bf16 v[64:79], v[222:225], v[124:127], v[64:79]
	ds_read_b128 v[218:221], v208 offset:49152
	ds_read_b128 v[222:225], v208 offset:57344
	s_waitcnt lgkmcnt(3)
	v_mfma_f32_32x32x16_bf16 v[80:95], v[240:243], v[112:115], v[80:95]
	s_waitcnt lgkmcnt(2)
	v_mfma_f32_32x32x16_bf16 v[64:79], v[246:249], v[112:115], v[64:79]
	v_cvt_pk_bf16_f32 v160, v175, v216
	v_cvt_pk_bf16_f32 v161, v161, v213
	v_cvt_pk_bf16_f32 v162, v162, v174
	v_cvt_pk_bf16_f32 v163, v163, v173
	v_cvt_pk_bf16_f32 v170, v170, v172
	v_cvt_pk_bf16_f32 v171, v169, v171
	s_waitcnt lgkmcnt(1)
	v_mfma_f32_32x32x16_bf16 v[80:95], v[218:221], v[120:123], v[80:95]
	v_cvt_pk_bf16_f32 v172, v166, v168
	v_cvt_pk_bf16_f32 v173, v165, v167
	v_cvt_pk_bf16_f32 v166, v156, v157
	v_cvt_pk_bf16_f32 v167, v154, v155
	v_cvt_pk_bf16_f32 v168, v148, v149
	v_cvt_pk_bf16_f32 v169, v146, v147
	v_cvt_pk_bf16_f32 v212, v144, v145
	s_waitcnt lgkmcnt(0)
	v_mfma_f32_32x32x16_bf16 v[64:79], v[222:225], v[120:123], v[64:79]
	v_cvt_pk_bf16_f32 v213, v158, v159
	v_cvt_pk_bf16_f32 v214, v152, v153
	v_permlane32_swap_b32_e32 v160, v162
	v_cvt_pk_bf16_f32 v215, v150, v151
	v_permlane32_swap_b32_e32 v212, v214
	v_permlane32_swap_b32_e32 v161, v163
	v_permlane32_swap_b32_e32 v170, v172
	v_permlane32_swap_b32_e32 v171, v173
	v_permlane32_swap_b32_e32 v166, v168
	v_permlane32_swap_b32_e32 v167, v169
	v_permlane32_swap_b32_e32 v213, v215
	s_mov_b32 s20, 0xfff10000
	v_add_co_u32_e32 v148, vcc, s20, v182
	s_mov_b32 s20, 0xfff60000
	s_nop 0
	v_addc_co_u32_e32 v149, vcc, -1, v183, vcc
	v_add_co_u32_e32 v152, vcc, s20, v182
	s_nop 1
	v_addc_co_u32_e32 v153, vcc, -1, v183, vcc
	v_add_co_u32_e32 v250, vcc, 0xfffb0000, v182
	s_nop 1
	v_addc_co_u32_e32 v251, vcc, -1, v183, vcc
	global_load_dwordx4 v[144:147], v[148:149], off
	s_nop 0
	global_load_dwordx4 v[148:151], v[250:251], off offset:-1024
	s_nop 0
	global_load_dwordx4 v[156:159], v[152:153], off
	s_nop 0
	global_load_dwordx4 v[152:155], v[182:183], off offset:-1024
	ds_read_b64_tr_b16 v[216:217], v191 offset:0
	ds_read_b64_tr_b16 v[218:219], v191 offset:0x800
	ds_read_b64_tr_b16 v[220:221], v191 offset:0x1000
	ds_read_b64_tr_b16 v[222:223], v191 offset:0x1800
	ds_read_b64_tr_b16 v[224:225], v191 offset:0x2000
	ds_read_b64_tr_b16 v[226:227], v191 offset:0x2800
	ds_read_b64_tr_b16 v[228:229], v191 offset:0x3000
	ds_read_b64_tr_b16 v[230:231], v191 offset:0x3800
	s_waitcnt lgkmcnt(0)
; #define SBAR() __builtin_amdgcn_sched_barrier(0)
; template <int D0> __device__ __forceinline__ void pv_one(f32x16& od, int vb, bf16x8 pa0, bf16x8 pa1, bf16x8 pa2, bf16x8 pa3) {
;   const s16x4 l0 = tr_read<v_rd_off(D0, 0, 0)>(vb), h0 = tr_read<v_rd_off(D0, 0, 1)>(vb), l1 = tr_read<v_rd_off(D0, 1, 0)>(vb), h1 = tr_read<v_rd_off(D0, 1, 1)>(vb);
;   const s16x4 l2 = tr_read<v_rd_off(D0, 2, 0)>(vb), h2 = tr_read<v_rd_off(D0, 2, 1)>(vb), l3 = tr_read<v_rd_off(D0, 3, 0)>(vb), h3 = tr_read<v_rd_off(D0, 3, 1)>(vb);
;   asm volatile("s_waitcnt lgkmcnt(0)" ::: "memory"); SBAR();
;     ...
;   od = __builtin_amdgcn_mfma_f32_32x32x16_bf16(pa0, PK(l0, h0), od, 0, 0, 0);
;   od = __builtin_amdgcn_mfma_f32_32x32x16_bf16(pa1, PK(l1, h1), od, 0, 0, 0);
;   od = __builtin_amdgcn_mfma_f32_32x32x16_bf16(pa2, PK(l2, h2), od, 0, 0, 0);
;   od = __builtin_amdgcn_mfma_f32_32x32x16_bf16(pa3, PK(l3, h3), od, 0, 0, 0);
;     ...
; }
; __device__ __forceinline__ void pv_d0(f32x16* o, int vb, bf16x8 pa0, bf16x8 pa1, bf16x8 pa2, bf16x8 pa3) {
;   pv_one<0>(o[0], vb, pa0, pa1, pa2, pa3); pv_one<1>(o[1], vb, pa0, pa1, pa2, pa3); pv_one<2>(o[2], vb, pa0, pa1, pa2, pa3); pv_one<3>(o[3], vb, pa0, pa1, pa2, pa3);
; }
	s_nop 0
	v_mfma_f32_32x32x16_bf16 v[0:15], v[160:163], v[216:219], v[0:15]
	ds_read_b64_tr_b16 v[216:217], v191 offset:0x200
	ds_read_b64_tr_b16 v[218:219], v191 offset:0xa00
	v_mfma_f32_32x32x16_bf16 v[0:15], v[170:173], v[220:223], v[0:15]
	ds_read_b64_tr_b16 v[220:221], v191 offset:0x1200
	ds_read_b64_tr_b16 v[222:223], v191 offset:0x1a00
	v_mfma_f32_32x32x16_bf16 v[0:15], v[166:169], v[224:227], v[0:15]
	ds_read_b64_tr_b16 v[224:225], v191 offset:0x2200
	ds_read_b64_tr_b16 v[226:227], v191 offset:0x2a00
	v_mfma_f32_32x32x16_bf16 v[0:15], v[212:215], v[228:231], v[0:15]
	ds_read_b64_tr_b16 v[228:229], v191 offset:0x3200
	ds_read_b64_tr_b16 v[230:231], v191 offset:0x3a00
	s_waitcnt lgkmcnt(0)
	v_mfma_f32_32x32x16_bf16 v[48:63], v[160:163], v[216:219], v[48:63]
	ds_read_b64_tr_b16 v[216:217], v191 offset:0x400
	ds_read_b64_tr_b16 v[218:219], v191 offset:0xc00
	v_mfma_f32_32x32x16_bf16 v[48:63], v[170:173], v[220:223], v[48:63]
	ds_read_b64_tr_b16 v[220:221], v191 offset:0x1400
	ds_read_b64_tr_b16 v[222:223], v191 offset:0x1c00
	v_mfma_f32_32x32x16_bf16 v[48:63], v[166:169], v[224:227], v[48:63]
	ds_read_b64_tr_b16 v[224:225], v191 offset:0x2400
	ds_read_b64_tr_b16 v[226:227], v191 offset:0x2c00
	v_mfma_f32_32x32x16_bf16 v[48:63], v[212:215], v[228:231], v[48:63]
	ds_read_b64_tr_b16 v[228:229], v191 offset:0x3400
	ds_read_b64_tr_b16 v[230:231], v191 offset:0x3c00
	s_waitcnt lgkmcnt(0)
	v_mfma_f32_32x32x16_bf16 v[32:47], v[160:163], v[216:219], v[32:47]
	ds_read_b64_tr_b16 v[216:217], v191 offset:0x600
	ds_read_b64_tr_b16 v[218:219], v191 offset:0xe00
	v_mfma_f32_32x32x16_bf16 v[32:47], v[170:173], v[220:223], v[32:47]
	ds_read_b64_tr_b16 v[220:221], v191 offset:0x1600
	ds_read_b64_tr_b16 v[222:223], v191 offset:0x1e00
	v_mfma_f32_32x32x16_bf16 v[32:47], v[166:169], v[224:227], v[32:47]
	ds_read_b64_tr_b16 v[224:225], v191 offset:0x2600
	ds_read_b64_tr_b16 v[226:227], v191 offset:0x2e00
	v_mfma_f32_32x32x16_bf16 v[32:47], v[212:215], v[228:231], v[32:47]
	ds_read_b64_tr_b16 v[228:229], v191 offset:0x3600
	ds_read_b64_tr_b16 v[230:231], v191 offset:0x3e00
	s_waitcnt lgkmcnt(0)
	v_mfma_f32_32x32x16_bf16 v[16:31], v[160:163], v[216:219], v[16:31]
	v_max_f32_e32 v160, v81, v81
	v_max_f32_e32 v161, v80, v80
	v_max_f32_e32 v160, v161, v160
	v_max3_f32 v160, v160, v82, v83
	v_max3_f32 v160, v160, v84, v85
	v_max3_f32 v160, v160, v86, v87
	v_max3_f32 v160, v160, v88, v89
	v_max3_f32 v160, v160, v90, v91
	v_max3_f32 v160, v160, v92, v93
	v_mfma_f32_32x32x16_bf16 v[16:31], v[170:173], v[220:223], v[16:31]
	v_max3_f32 v160, v160, v94, v95
	v_max3_f32 v160, v160, v64, v65
	v_max3_f32 v160, v160, v66, v67
	v_max3_f32 v160, v160, v68, v69
	v_max3_f32 v160, v160, v70, v71
	v_max3_f32 v160, v160, v72, v73
	v_max3_f32 v160, v160, v74, v75
	v_max3_f32 v160, v160, v76, v77
	v_mfma_f32_32x32x16_bf16 v[16:31], v[166:169], v[224:227], v[16:31]
	v_max3_f32 v160, v160, v78, v79
	v_mov_b32_e32 v161, v160
	s_nop 1
	v_permlane32_swap_b32_e32 v160, v161
	v_max_f32_e32 v161, v161, v161
	v_max_f32_e32 v160, v160, v160
	v_max_f32_e32 v160, v160, v161
	v_sub_f32_e32 v161, v160, v164
	v_cmp_ge_f32_e32 vcc, s71, v161
	v_max_f32_e32 v161, v164, v164
	v_max_f32_e32 v160, v161, v160
	v_mfma_f32_32x32x16_bf16 v[16:31], v[212:215], v[228:231], v[16:31]
	v_sub_f32_e32 v161, v164, v160
	v_mul_f32_e32 v161, 0x3e0293ee, v161
	v_exp_f32_e32 v161, v161
	s_cmp_eq_u64 vcc, exec
	s_cselect_b64 s[38:39], -1, 0
	s_barrier
	s_waitcnt vmcnt(4)
	v_cndmask_b32_e64 v212, v161, 1.0, s[38:39]
	v_cmp_gt_f32_e32 vcc, 1.0, v212
	s_waitcnt vmcnt(7)
	ds_write_b128 v192, v[128:131]
	s_waitcnt vmcnt(6)
	ds_write_b128 v193, v[132:135]
	s_waitcnt vmcnt(5)
	ds_write_b128 v199, v[136:139] offset:49152
	s_waitcnt vmcnt(4)
	ds_write_b128 v200, v[140:143] offset:49152
	s_cbranch_vccz .LBB0_263
	s_and_saveexec_b64 s[42:43], s[36:37]
	ds_write_b32 v188, v212 offset:128
	s_or_b64 exec, exec, s[42:43]
	s_waitcnt lgkmcnt(0)
	v_add_u32_e32 v161, v187, v176
	ds_read_b128 v[166:169], v161 offset:224
	ds_read_b128 v[170:173], v161 offset:192
	ds_read_b128 v[214:217], v161 offset:160
	ds_read_b128 v[218:221], v161 offset:128
	s_waitcnt lgkmcnt(3)
	v_pk_mul_f32 v[12:13], v[12:13], v[166:167]
	s_waitcnt lgkmcnt(2)
	v_pk_mul_f32 v[8:9], v[8:9], v[170:171]
	s_waitcnt lgkmcnt(1)
	v_pk_mul_f32 v[4:5], v[4:5], v[214:215]
	v_pk_mul_f32 v[14:15], v[14:15], v[168:169]
	v_pk_mul_f32 v[10:11], v[10:11], v[172:173]
	v_pk_mul_f32 v[6:7], v[6:7], v[216:217]
	s_waitcnt lgkmcnt(0)
	v_pk_mul_f32 v[2:3], v[2:3], v[220:221]
	v_pk_mul_f32 v[0:1], v[0:1], v[218:219]
	v_pk_mul_f32 v[60:61], v[60:61], v[166:167]
	v_pk_mul_f32 v[56:57], v[56:57], v[170:171]
	v_pk_mul_f32 v[52:53], v[52:53], v[214:215]
	v_pk_mul_f32 v[62:63], v[62:63], v[168:169]
	v_pk_mul_f32 v[58:59], v[58:59], v[172:173]
	v_pk_mul_f32 v[54:55], v[54:55], v[216:217]
	v_pk_mul_f32 v[50:51], v[50:51], v[220:221]
	v_pk_mul_f32 v[48:49], v[48:49], v[218:219]
	v_pk_mul_f32 v[44:45], v[44:45], v[166:167]
	v_pk_mul_f32 v[40:41], v[40:41], v[170:171]
	v_pk_mul_f32 v[36:37], v[36:37], v[214:215]
	v_pk_mul_f32 v[46:47], v[46:47], v[168:169]
	v_pk_mul_f32 v[42:43], v[42:43], v[172:173]
	v_pk_mul_f32 v[38:39], v[38:39], v[216:217]
	v_pk_mul_f32 v[34:35], v[34:35], v[220:221]
	v_pk_mul_f32 v[32:33], v[32:33], v[218:219]
	v_pk_mul_f32 v[28:29], v[28:29], v[166:167]
	v_pk_mul_f32 v[24:25], v[24:25], v[170:171]
	v_pk_mul_f32 v[20:21], v[20:21], v[214:215]
	v_pk_mul_f32 v[30:31], v[30:31], v[168:169]
	v_pk_mul_f32 v[26:27], v[26:27], v[172:173]
	v_pk_mul_f32 v[22:23], v[22:23], v[216:217]
	v_pk_mul_f32 v[18:19], v[18:19], v[220:221]
	v_pk_mul_f32 v[16:17], v[16:17], v[218:219]
; __device__ __forceinline__ void partialSM(f32x16& p0, f32x16& p1, float& m_reg, float& mn, float& alpha) {
;     ...
;   float mnC = -mn * C;
;   for (int r = 0; r < 16; ++r) p0[r] = fmaf(p0[r], C, mnC); for (int r = 0; r < 16; ++r) p1[r] = fmaf(p1[r], C, mnC);
;   for (int r = 0; r < 16; ++r) p0[r] = __builtin_amdgcn_exp2f(p0[r]);
; }
; __device__ __forceinline__ void finishSM(f32x16& p0, f32x16& p1, float alpha, float& l_reg, bf16x8& pa0, bf16x8& pa1, bf16x8& pa2, bf16x8& pa3) {
;   for (int r = 0; r < 16; ++r) p1[r] = __builtin_amdgcn_exp2f(p1[r]);
;   float ps = 0; for (int r = 0; r < 16; ++r) ps += p0[r]; for (int r = 0; r < 16; ++r) ps += p1[r];
;   { auto rr = __builtin_amdgcn_permlane32_swap(__float_as_uint(ps), __float_as_uint(ps), false, false);
;     ps = __uint_as_float(rr[0]) + __uint_as_float(rr[1]); }
;   l_reg = l_reg * alpha + ps;
;     ...
;   PK4(p0, 0, pa0); PK4(p0, 8, pa1); PK4(p1, 0, pa2); PK4(p1, 8, pa3);
;     ...
; }
; __device__ __forceinline__ void qkt(f32x16& p0, f32x16& p1, const char* Ks, const bf16x8* qr, int r32, int hi) {
;   p0 = f32x16{}; p1 = f32x16{};
;   for (int d0 = 0; d0 < 8; ++d0) { int cb = (d0 * 16 + hi * 8) * 2;
;     bf16x8 b0 = *reinterpret_cast<const bf16x8*>(Ks + KSWZ(r32, cb));
;     bf16x8 b1 = *reinterpret_cast<const bf16x8*>(Ks + KSWZ(32 + r32, cb));
;     p0 = __builtin_amdgcn_mfma_f32_32x32x16_bf16(b0, qr[d0], p0, 0, 0, 0);
;     p1 = __builtin_amdgcn_mfma_f32_32x32x16_bf16(b1, qr[d0], p1, 0, 0, 0); }
; }
.LBB0_263:
	v_cndmask_b32_e64 v213, v160, v164, s[38:39]
	v_mul_f32_e32 v214, 0xbe0293ee, v213
	v_fmamk_f32 v80, v80, 0x3e0293ee, v214
	v_fmamk_f32 v81, v81, 0x3e0293ee, v214
	v_fmamk_f32 v82, v82, 0x3e0293ee, v214
	v_fmamk_f32 v83, v83, 0x3e0293ee, v214
	v_fmamk_f32 v84, v84, 0x3e0293ee, v214
	v_fmamk_f32 v85, v85, 0x3e0293ee, v214
	v_fmamk_f32 v86, v86, 0x3e0293ee, v214
	v_fmamk_f32 v87, v87, 0x3e0293ee, v214
	v_fmamk_f32 v88, v88, 0x3e0293ee, v214
	v_fmamk_f32 v89, v89, 0x3e0293ee, v214
	v_fmamk_f32 v90, v90, 0x3e0293ee, v214
	v_fmamk_f32 v91, v91, 0x3e0293ee, v214
	v_fmamk_f32 v92, v92, 0x3e0293ee, v214
	v_fmamk_f32 v93, v93, 0x3e0293ee, v214
	v_fmamk_f32 v94, v94, 0x3e0293ee, v214
	v_fmamk_f32 v95, v95, 0x3e0293ee, v214
	v_exp_f32_e32 v160, v80
	v_exp_f32_e32 v175, v81
	v_exp_f32_e32 v161, v82
	v_exp_f32_e32 v174, v83
	v_exp_f32_e32 v162, v84
	v_exp_f32_e32 v173, v85
	v_exp_f32_e32 v163, v86
	v_exp_f32_e32 v172, v87
	v_exp_f32_e32 v164, v88
	v_exp_f32_e32 v171, v89
	v_exp_f32_e32 v165, v90
	v_exp_f32_e32 v170, v91
	v_exp_f32_e32 v166, v92
	v_exp_f32_e32 v169, v93
	v_exp_f32_e32 v167, v94
	v_exp_f32_e32 v168, v95
	v_fmamk_f32 v223, v64, 0x3e0293ee, v214
	v_fmamk_f32 v224, v65, 0x3e0293ee, v214
	v_fmamk_f32 v225, v66, 0x3e0293ee, v214
	v_fmamk_f32 v226, v67, 0x3e0293ee, v214
	v_fmamk_f32 v227, v68, 0x3e0293ee, v214
	v_fmamk_f32 v216, v69, 0x3e0293ee, v214
	v_fmamk_f32 v217, v70, 0x3e0293ee, v214
	v_fmamk_f32 v218, v71, 0x3e0293ee, v214
	v_fmamk_f32 v219, v72, 0x3e0293ee, v214
	v_fmamk_f32 v220, v73, 0x3e0293ee, v214
	v_fmamk_f32 v221, v74, 0x3e0293ee, v214
	v_fmamk_f32 v222, v75, 0x3e0293ee, v214
	v_fmamk_f32 v215, v76, 0x3e0293ee, v214
	v_fmamk_f32 v228, v77, 0x3e0293ee, v214
	v_fmamk_f32 v229, v78, 0x3e0293ee, v214
	v_fmac_f32_e32 v214, 0x3e0293ee, v79
	s_add_i32 s19, s19, 2
	s_waitcnt lgkmcnt(0)
	ds_read_b128 v[64:67], v201 offset:32768
	ds_read_b128 v[68:71], v201 offset:40960
	ds_read_b128 v[230:233], v204 offset:32768
	ds_read_b128 v[234:237], v204 offset:40960
	ds_read_b128 v[240:243], v205 offset:32768
	ds_read_b128 v[246:249], v205 offset:40960
	v_exp_f32_e32 v194, v223
	v_exp_f32_e32 v223, v227
	s_waitcnt lgkmcnt(5)
	v_mfma_f32_32x32x16_bf16 v[80:95], v[64:67], v[100:103], 0
	v_exp_f32_e32 v227, v214
	v_add_f32_e32 v214, 0, v160
	v_add_f32_e32 v214, v175, v214
	v_add_f32_e32 v214, v161, v214
	v_add_f32_e32 v214, v174, v214
	v_add_f32_e32 v214, v162, v214
	v_add_f32_e32 v214, v173, v214
	s_waitcnt lgkmcnt(4)
	v_mfma_f32_32x32x16_bf16 v[64:79], v[68:71], v[100:103], 0
	v_add_f32_e32 v214, v163, v214
	v_add_f32_e32 v214, v172, v214
	v_add_f32_e32 v214, v164, v214
	v_add_f32_e32 v214, v171, v214
	v_add_f32_e32 v214, v165, v214
	v_add_f32_e32 v214, v170, v214
	v_add_f32_e32 v214, v166, v214
	s_waitcnt lgkmcnt(3)
	v_mfma_f32_32x32x16_bf16 v[80:95], v[230:233], v[108:111], v[80:95]
	v_exp_f32_e32 v195, v224
	v_add_f32_e32 v214, v169, v214
	v_exp_f32_e32 v196, v225
	v_add_f32_e32 v214, v167, v214
	v_exp_f32_e32 v197, v226
	v_add_f32_e32 v214, v168, v214
	v_add_f32_e32 v214, v194, v214
	s_waitcnt lgkmcnt(2)
	v_mfma_f32_32x32x16_bf16 v[64:79], v[234:237], v[108:111], v[64:79]
	ds_read_b128 v[230:233], v202 offset:32768
	ds_read_b128 v[234:237], v202 offset:40960
	v_exp_f32_e32 v216, v216
	v_add_f32_e32 v214, v195, v214
	v_exp_f32_e32 v217, v217
	v_add_f32_e32 v214, v196, v214
	v_exp_f32_e32 v218, v218
	v_add_f32_e32 v214, v197, v214
	s_waitcnt lgkmcnt(3)
	v_mfma_f32_32x32x16_bf16 v[80:95], v[240:243], v[96:99], v[80:95]
	v_exp_f32_e32 v219, v219
	v_add_f32_e32 v214, v223, v214
	v_exp_f32_e32 v220, v220
	v_add_f32_e32 v214, v216, v214
	v_exp_f32_e32 v221, v221
	v_add_f32_e32 v214, v217, v214
	v_exp_f32_e32 v222, v222
	s_waitcnt lgkmcnt(2)
	v_mfma_f32_32x32x16_bf16 v[64:79], v[246:249], v[96:99], v[64:79]
	ds_read_b128 v[240:243], v203 offset:32768
	ds_read_b128 v[246:249], v203 offset:40960
	v_add_f32_e32 v214, v218, v214
	v_exp_f32_e32 v224, v215
	v_add_f32_e32 v214, v219, v214
	v_exp_f32_e32 v225, v228
	v_add_f32_e32 v214, v220, v214
	v_exp_f32_e32 v226, v229
	s_waitcnt lgkmcnt(3)
	v_mfma_f32_32x32x16_bf16 v[80:95], v[230:233], v[104:107], v[80:95]
	v_add_f32_e32 v214, v221, v214
	v_add_f32_e32 v214, v222, v214
	v_add_f32_e32 v214, v224, v214
	v_add_f32_e32 v214, v225, v214
	v_add_f32_e32 v214, v226, v214
	v_add_f32_e32 v214, v227, v214
	v_mov_b32_e32 v215, v214
	s_waitcnt lgkmcnt(2)
	v_mfma_f32_32x32x16_bf16 v[64:79], v[234:237], v[104:107], v[64:79]
	ds_read_b128 v[230:233], v206 offset:32768
	ds_read_b128 v[234:237], v206 offset:40960
	v_permlane32_swap_b32_e32 v214, v215
	s_waitcnt lgkmcnt(3)
	v_mfma_f32_32x32x16_bf16 v[80:95], v[240:243], v[116:119], v[80:95]
	s_waitcnt lgkmcnt(2)
	v_mfma_f32_32x32x16_bf16 v[64:79], v[246:249], v[116:119], v[64:79]
	ds_read_b128 v[240:243], v207 offset:32768
	ds_read_b128 v[246:249], v207 offset:40960
	s_waitcnt lgkmcnt(3)
	v_mfma_f32_32x32x16_bf16 v[80:95], v[230:233], v[124:127], v[80:95]
	s_waitcnt lgkmcnt(2)
	v_mfma_f32_32x32x16_bf16 v[64:79], v[234:237], v[124:127], v[64:79]
	ds_read_b128 v[230:233], v208 offset:32768
	ds_read_b128 v[234:237], v208 offset:40960
	s_waitcnt lgkmcnt(3)
	v_mfma_f32_32x32x16_bf16 v[80:95], v[240:243], v[112:115], v[80:95]
	s_waitcnt lgkmcnt(2)
	v_mfma_f32_32x32x16_bf16 v[64:79], v[246:249], v[112:115], v[64:79]
	v_cvt_pk_bf16_f32 v160, v160, v175
	v_cvt_pk_bf16_f32 v161, v161, v174
	v_cvt_pk_bf16_f32 v162, v162, v173
	v_cvt_pk_bf16_f32 v163, v163, v172
	v_cvt_pk_bf16_f32 v164, v164, v171
	v_cvt_pk_bf16_f32 v165, v165, v170
	s_waitcnt lgkmcnt(1)
	v_mfma_f32_32x32x16_bf16 v[80:95], v[230:233], v[120:123], v[80:95]
	v_cvt_pk_bf16_f32 v166, v166, v169
	v_cvt_pk_bf16_f32 v167, v167, v168
	v_cvt_pk_bf16_f32 v168, v194, v195
	v_cvt_pk_bf16_f32 v169, v196, v197
	v_cvt_pk_bf16_f32 v170, v223, v216
	v_cvt_pk_bf16_f32 v171, v217, v218
	v_cvt_pk_bf16_f32 v172, v219, v220
	s_waitcnt lgkmcnt(0)
	v_mfma_f32_32x32x16_bf16 v[64:79], v[234:237], v[120:123], v[64:79]
	v_cvt_pk_bf16_f32 v173, v221, v222
	v_cvt_pk_bf16_f32 v174, v224, v225
	v_cvt_pk_bf16_f32 v175, v226, v227
	v_permlane32_swap_b32_e32 v160, v162
	v_permlane32_swap_b32_e32 v161, v163
	v_permlane32_swap_b32_e32 v164, v166
	v_permlane32_swap_b32_e32 v165, v167
	v_permlane32_swap_b32_e32 v168, v170
	v_permlane32_swap_b32_e32 v169, v171
	v_permlane32_swap_b32_e32 v172, v174
	v_permlane32_swap_b32_e32 v173, v175
	s_cmp_gt_u32 s19, 60
	s_cselect_b64 s[42:43], -1, 0
	s_and_b64 vcc, exec, s[42:43]
	s_cbranch_vccnz .LBB0_265
	v_add_co_u32_e32 v132, vcc, 0xfffb0000, v182
	s_nop 1
	v_addc_co_u32_e32 v133, vcc, -1, v183, vcc
	v_add_co_u32_e32 v250, vcc, 0x50000, v182
	s_nop 1
	v_addc_co_u32_e32 v251, vcc, 0, v183, vcc
	global_load_dwordx4 v[128:131], v[132:133], off
	global_load_dwordx4 v[136:139], v[250:251], off offset:-1024
	s_nop 0
	global_load_dwordx4 v[132:135], v[182:183], off
	v_add_co_u32_e32 v250, vcc, 0xa0000, v182
	s_nop 1
	v_addc_co_u32_e32 v251, vcc, 0, v183, vcc
	global_load_dwordx4 v[140:143], v[250:251], off offset:-1024
; #define SBAR() __builtin_amdgcn_sched_barrier(0)
; template <int D0> __device__ __forceinline__ void pv_one(f32x16& od, int vb, bf16x8 pa0, bf16x8 pa1, bf16x8 pa2, bf16x8 pa3) {
;   const s16x4 l0 = tr_read<v_rd_off(D0, 0, 0)>(vb), h0 = tr_read<v_rd_off(D0, 0, 1)>(vb), l1 = tr_read<v_rd_off(D0, 1, 0)>(vb), h1 = tr_read<v_rd_off(D0, 1, 1)>(vb);
;   const s16x4 l2 = tr_read<v_rd_off(D0, 2, 0)>(vb), h2 = tr_read<v_rd_off(D0, 2, 1)>(vb), l3 = tr_read<v_rd_off(D0, 3, 0)>(vb), h3 = tr_read<v_rd_off(D0, 3, 1)>(vb);
;   asm volatile("s_waitcnt lgkmcnt(0)" ::: "memory"); SBAR();
;     ...
;   od = __builtin_amdgcn_mfma_f32_32x32x16_bf16(pa0, PK(l0, h0), od, 0, 0, 0);
;   od = __builtin_amdgcn_mfma_f32_32x32x16_bf16(pa1, PK(l1, h1), od, 0, 0, 0);
;   od = __builtin_amdgcn_mfma_f32_32x32x16_bf16(pa2, PK(l2, h2), od, 0, 0, 0);
;   od = __builtin_amdgcn_mfma_f32_32x32x16_bf16(pa3, PK(l3, h3), od, 0, 0, 0);
;     ...
; }
; __device__ __forceinline__ void pv_d0(f32x16* o, int vb, bf16x8 pa0, bf16x8 pa1, bf16x8 pa2, bf16x8 pa3) {
;   pv_one<0>(o[0], vb, pa0, pa1, pa2, pa3); pv_one<1>(o[1], vb, pa0, pa1, pa2, pa3); pv_one<2>(o[2], vb, pa0, pa1, pa2, pa3); pv_one<3>(o[3], vb, pa0, pa1, pa2, pa3);
; }
.LBB0_265:
	ds_read_b64_tr_b16 v[216:217], v190 offset:0
	ds_read_b64_tr_b16 v[218:219], v190 offset:0x800
	ds_read_b64_tr_b16 v[220:221], v190 offset:0x1000
	ds_read_b64_tr_b16 v[222:223], v190 offset:0x1800
	ds_read_b64_tr_b16 v[224:225], v190 offset:0x2000
	ds_read_b64_tr_b16 v[226:227], v190 offset:0x2800
	ds_read_b64_tr_b16 v[228:229], v190 offset:0x3000
	ds_read_b64_tr_b16 v[230:231], v190 offset:0x3800
	s_waitcnt lgkmcnt(0)
	s_nop 0
	v_mfma_f32_32x32x16_bf16 v[0:15], v[160:163], v[216:219], v[0:15]
	ds_read_b64_tr_b16 v[216:217], v190 offset:0x200
	ds_read_b64_tr_b16 v[218:219], v190 offset:0xa00
	v_mfma_f32_32x32x16_bf16 v[0:15], v[164:167], v[220:223], v[0:15]
	ds_read_b64_tr_b16 v[220:221], v190 offset:0x1200
	ds_read_b64_tr_b16 v[222:223], v190 offset:0x1a00
	v_mfma_f32_32x32x16_bf16 v[0:15], v[168:171], v[224:227], v[0:15]
	ds_read_b64_tr_b16 v[224:225], v190 offset:0x2200
	ds_read_b64_tr_b16 v[226:227], v190 offset:0x2a00
	v_mfma_f32_32x32x16_bf16 v[0:15], v[172:175], v[228:231], v[0:15]
	ds_read_b64_tr_b16 v[228:229], v190 offset:0x3200
	ds_read_b64_tr_b16 v[230:231], v190 offset:0x3a00
	s_waitcnt lgkmcnt(0)
	v_mfma_f32_32x32x16_bf16 v[48:63], v[160:163], v[216:219], v[48:63]
	ds_read_b64_tr_b16 v[216:217], v190 offset:0x400
	ds_read_b64_tr_b16 v[218:219], v190 offset:0xc00
	v_mfma_f32_32x32x16_bf16 v[48:63], v[164:167], v[220:223], v[48:63]
	ds_read_b64_tr_b16 v[220:221], v190 offset:0x1400
	ds_read_b64_tr_b16 v[222:223], v190 offset:0x1c00
	v_mfma_f32_32x32x16_bf16 v[48:63], v[168:171], v[224:227], v[48:63]
	ds_read_b64_tr_b16 v[224:225], v190 offset:0x2400
	ds_read_b64_tr_b16 v[226:227], v190 offset:0x2c00
	v_mfma_f32_32x32x16_bf16 v[48:63], v[172:175], v[228:231], v[48:63]
	ds_read_b64_tr_b16 v[228:229], v190 offset:0x3400
	ds_read_b64_tr_b16 v[230:231], v190 offset:0x3c00
	s_waitcnt lgkmcnt(0)
	v_mfma_f32_32x32x16_bf16 v[32:47], v[160:163], v[216:219], v[32:47]
	ds_read_b64_tr_b16 v[216:217], v190 offset:0x600
	ds_read_b64_tr_b16 v[218:219], v190 offset:0xe00
	v_mfma_f32_32x32x16_bf16 v[32:47], v[164:167], v[220:223], v[32:47]
	ds_read_b64_tr_b16 v[220:221], v190 offset:0x1600
	ds_read_b64_tr_b16 v[222:223], v190 offset:0x1e00
	v_mfma_f32_32x32x16_bf16 v[32:47], v[168:171], v[224:227], v[32:47]
	ds_read_b64_tr_b16 v[224:225], v190 offset:0x2600
	ds_read_b64_tr_b16 v[226:227], v190 offset:0x2e00
	v_mfma_f32_32x32x16_bf16 v[32:47], v[172:175], v[228:231], v[32:47]
	ds_read_b64_tr_b16 v[228:229], v190 offset:0x3600
	ds_read_b64_tr_b16 v[230:231], v190 offset:0x3e00
	s_waitcnt lgkmcnt(0)
	v_mfma_f32_32x32x16_bf16 v[16:31], v[160:163], v[216:219], v[16:31]
	v_max_f32_e32 v160, v81, v81
	v_max_f32_e32 v161, v80, v80
	v_max_f32_e32 v160, v161, v160
	v_max3_f32 v160, v160, v82, v83
	v_max3_f32 v160, v160, v84, v85
	v_max3_f32 v160, v160, v86, v87
	v_max3_f32 v160, v160, v88, v89
	v_max3_f32 v160, v160, v90, v91
	v_max3_f32 v160, v160, v92, v93
	v_mfma_f32_32x32x16_bf16 v[16:31], v[164:167], v[220:223], v[16:31]
	v_max3_f32 v160, v160, v94, v95
	v_max3_f32 v160, v160, v64, v65
	v_max3_f32 v160, v160, v66, v67
	v_max3_f32 v160, v160, v68, v69
	v_max3_f32 v160, v160, v70, v71
	v_max3_f32 v160, v160, v72, v73
	v_max3_f32 v160, v160, v74, v75
	v_max3_f32 v160, v160, v76, v77
	v_mfma_f32_32x32x16_bf16 v[16:31], v[168:171], v[224:227], v[16:31]
	v_max3_f32 v160, v160, v78, v79
	v_mov_b32_e32 v161, v160
	s_nop 1
	v_permlane32_swap_b32_e32 v160, v161
	v_max_f32_e32 v161, v161, v161
	v_max_f32_e32 v160, v160, v160
	v_max_f32_e32 v160, v160, v161
	v_sub_f32_e32 v161, v160, v213
	v_cmp_ge_f32_e32 vcc, s71, v161
	v_max_f32_e32 v161, v213, v213
	v_max_f32_e32 v161, v161, v160
	v_mfma_f32_32x32x16_bf16 v[16:31], v[172:175], v[228:231], v[16:31]
	v_sub_f32_e32 v160, v213, v161
	v_mul_f32_e32 v160, 0x3e0293ee, v160
	v_exp_f32_e32 v160, v160
	s_cmp_eq_u64 vcc, exec
	s_cselect_b64 s[38:39], -1, 0
	s_barrier
	s_waitcnt vmcnt(4)
	v_cndmask_b32_e64 v160, v160, 1.0, s[38:39]
	v_cmp_gt_f32_e32 vcc, 1.0, v160
	s_waitcnt vmcnt(3)
	ds_write_b128 v192, v[144:147] offset:16384
	s_waitcnt vmcnt(1)
	ds_write_b128 v193, v[156:159] offset:16384
	ds_write_b128 v199, v[148:151] offset:32768
	s_waitcnt vmcnt(0)
	ds_write_b128 v200, v[152:155] offset:32768
	s_cbranch_vccz .LBB0_269
	s_and_saveexec_b64 s[44:45], s[36:37]
	ds_write_b32 v188, v160 offset:128
	s_or_b64 exec, exec, s[44:45]
	s_waitcnt lgkmcnt(0)
	v_add_u32_e32 v156, v187, v176
	ds_read_b128 v[144:147], v156 offset:224
	ds_read_b128 v[148:151], v156 offset:192
	ds_read_b128 v[152:155], v156 offset:160
	ds_read_b128 v[156:159], v156 offset:128
	s_waitcnt lgkmcnt(3)
	v_pk_mul_f32 v[12:13], v[12:13], v[144:145]
	s_waitcnt lgkmcnt(2)
	v_pk_mul_f32 v[8:9], v[8:9], v[148:149]
	s_waitcnt lgkmcnt(1)
	v_pk_mul_f32 v[4:5], v[4:5], v[152:153]
	v_pk_mul_f32 v[14:15], v[14:15], v[146:147]
	v_pk_mul_f32 v[10:11], v[10:11], v[150:151]
	v_pk_mul_f32 v[6:7], v[6:7], v[154:155]
	s_waitcnt lgkmcnt(0)
	v_pk_mul_f32 v[2:3], v[2:3], v[158:159]
	v_pk_mul_f32 v[0:1], v[0:1], v[156:157]
	v_pk_mul_f32 v[60:61], v[60:61], v[144:145]
	v_pk_mul_f32 v[56:57], v[56:57], v[148:149]
	v_pk_mul_f32 v[52:53], v[52:53], v[152:153]
	v_pk_mul_f32 v[62:63], v[62:63], v[146:147]
	v_pk_mul_f32 v[58:59], v[58:59], v[150:151]
	v_pk_mul_f32 v[54:55], v[54:55], v[154:155]
	v_pk_mul_f32 v[50:51], v[50:51], v[158:159]
	v_pk_mul_f32 v[48:49], v[48:49], v[156:157]
	v_pk_mul_f32 v[44:45], v[44:45], v[144:145]
	v_pk_mul_f32 v[40:41], v[40:41], v[148:149]
	v_pk_mul_f32 v[36:37], v[36:37], v[152:153]
	v_pk_mul_f32 v[46:47], v[46:47], v[146:147]
	v_pk_mul_f32 v[42:43], v[42:43], v[150:151]
	v_pk_mul_f32 v[38:39], v[38:39], v[154:155]
	v_pk_mul_f32 v[34:35], v[34:35], v[158:159]
	v_pk_mul_f32 v[32:33], v[32:33], v[156:157]
	v_pk_mul_f32 v[28:29], v[28:29], v[144:145]
	v_pk_mul_f32 v[24:25], v[24:25], v[148:149]
	v_pk_mul_f32 v[20:21], v[20:21], v[152:153]
	v_pk_mul_f32 v[30:31], v[30:31], v[146:147]
	v_pk_mul_f32 v[26:27], v[26:27], v[150:151]
	v_pk_mul_f32 v[22:23], v[22:23], v[154:155]
	v_pk_mul_f32 v[18:19], v[18:19], v[158:159]
	v_pk_mul_f32 v[16:17], v[16:17], v[156:157]
; __device__ __forceinline__ void partialSM(f32x16& p0, f32x16& p1, float& m_reg, float& mn, float& alpha) {
;     ...
;   float mnC = -mn * C;
;   for (int r = 0; r < 16; ++r) p0[r] = fmaf(p0[r], C, mnC); for (int r = 0; r < 16; ++r) p1[r] = fmaf(p1[r], C, mnC);
;   for (int r = 0; r < 16; ++r) p0[r] = __builtin_amdgcn_exp2f(p0[r]);
; }
; __device__ __forceinline__ void finishSM(f32x16& p0, f32x16& p1, float alpha, float& l_reg, bf16x8& pa0, bf16x8& pa1, bf16x8& pa2, bf16x8& pa3) {
;   for (int r = 0; r < 16; ++r) p1[r] = __builtin_amdgcn_exp2f(p1[r]);
;   float ps = 0; for (int r = 0; r < 16; ++r) ps += p0[r]; for (int r = 0; r < 16; ++r) ps += p1[r];
;   { auto rr = __builtin_amdgcn_permlane32_swap(__float_as_uint(ps), __float_as_uint(ps), false, false);
;     ps = __uint_as_float(rr[0]) + __uint_as_float(rr[1]); }
;   l_reg = l_reg * alpha + ps;
.LBB0_269:
	v_cndmask_b32_e64 v164, v161, v213, s[38:39]
	v_mul_f32_e32 v150, 0xbe0293ee, v164
	v_mov_b32_e32 v151, v150
	v_fmamk_f32 v80, v80, 0x3e0293ee, v150
	v_fmamk_f32 v81, v81, 0x3e0293ee, v150
	v_fmamk_f32 v82, v82, 0x3e0293ee, v150
	v_fmamk_f32 v83, v83, 0x3e0293ee, v150
	v_fmamk_f32 v84, v84, 0x3e0293ee, v150
	v_fmamk_f32 v85, v85, 0x3e0293ee, v150
	v_fmamk_f32 v86, v86, 0x3e0293ee, v150
	v_fmamk_f32 v87, v87, 0x3e0293ee, v150
	v_fmamk_f32 v88, v88, 0x3e0293ee, v150
	v_fmamk_f32 v89, v89, 0x3e0293ee, v150
	v_fmamk_f32 v90, v90, 0x3e0293ee, v150
	v_fmamk_f32 v91, v91, 0x3e0293ee, v150
	v_fmamk_f32 v92, v92, 0x3e0293ee, v150
	v_fmamk_f32 v93, v93, 0x3e0293ee, v150
	v_fmamk_f32 v94, v94, 0x3e0293ee, v150
	v_fmac_f32_e32 v151, 0x3e0293ee, v95
	v_exp_f32_e32 v175, v80
	v_exp_f32_e32 v216, v81
	v_exp_f32_e32 v161, v82
	v_exp_f32_e32 v213, v83
	v_exp_f32_e32 v162, v84
	v_exp_f32_e32 v174, v85
	v_exp_f32_e32 v163, v86
	v_exp_f32_e32 v173, v87
	v_exp_f32_e32 v170, v88
	v_exp_f32_e32 v172, v89
	v_exp_f32_e32 v169, v90
	v_exp_f32_e32 v171, v91
	v_exp_f32_e32 v166, v92
	v_exp_f32_e32 v168, v93
	v_exp_f32_e32 v165, v94
	v_exp_f32_e32 v167, v151
	v_pk_fma_f32 v[156:157], v[64:65], s[62:63], v[150:151] op_sel_hi:[1,0,0]
	v_add_f32_e32 v64, v210, v211
	v_fmac_f32_e32 v64, v209, v189
	v_add_f32_e32 v189, v214, v215
	s_mov_b64 s[20:21], 0x140000
	v_pk_fma_f32 v[154:155], v[66:67], s[62:63], v[150:151] op_sel_hi:[1,0,0]
	v_pk_fma_f32 v[148:149], v[68:69], s[62:63], v[150:151] op_sel_hi:[1,0,0]
	v_pk_fma_f32 v[146:147], v[70:71], s[62:63], v[150:151] op_sel_hi:[1,0,0]
	v_pk_fma_f32 v[144:145], v[72:73], s[62:63], v[150:151] op_sel_hi:[1,0,0]
	v_pk_fma_f32 v[158:159], v[74:75], s[62:63], v[150:151] op_sel_hi:[1,0,0]
	v_pk_fma_f32 v[152:153], v[76:77], s[62:63], v[150:151] op_sel_hi:[1,0,0]
	v_pk_fma_f32 v[150:151], v[78:79], s[62:63], v[150:151] op_sel_hi:[1,0,0]
	v_fmac_f32_e32 v189, v64, v212
	v_lshl_add_u64 v[182:183], v[182:183], 0, s[20:21]
	s_and_b64 vcc, exec, s[42:43]
	s_waitcnt lgkmcnt(0)
	s_cbranch_vccnz .LBB0_271
	v_mov_b32_e32 v209, v160
	s_branch .LBB0_259
